# SCAN1: P-role waves no longer rebuild the operand images / M matrix; they read the U-role partner wave's LDS images (3 workgroup barriers per 16-step sub-block)
# baseline (speedup 1.0000x reference)
; #define RAW2(w) ((f32x2){__uint_as_float((w) << 16), __uint_as_float((w) & 0xffff0000u)})
; template <int role> __device__ __forceinline__ void ph_scan1m_r(Ctx& C) {
;     ...
;             const int par = lane >> 5, c0 = 2 * (lane & 31), cme = c0 + par; const float pm = par ? 1.44269504f : 0.f;
;             f32x2 Lm[8], Lt[8], GT2;
;             { f32x2 bef = (f32x2){0.f, 0.f};
; #pragma unroll
;               for (int j = 0; j < 8; ++j) { auto sw = __builtin_amdgcn_permlane32_swap(rl[j], rl[j], false, false); asm volatile("s_nop 1" : "+v"(sw[0]), "+v"(sw[1]));
;                   const f32x2 e = RAW2(sw[0]), o = RAW2(sw[1]); const f32x2 be = bef + e;
;                   Lm[j] = bef * 1.44269504f + e * pm; Lt[j] = be * 1.44269504f + o * pm; bef = be + o; }
;               GT2 = (f32x2){__builtin_amdgcn_exp2f(bef.x * 1.44269504f), __builtin_amdgcn_exp2f(bef.y * 1.44269504f)}; }
.LBB0_709:
	s_waitcnt vmcnt(47)
	v_mov_b32_e32 v65, v142
	v_mov_b32_e32 v69, v142
	v_mov_b32_e32 v112, v140
	s_nop 0
	v_permlane32_swap_b32_e32 v65, v69
	s_waitcnt vmcnt(2)
	s_nop 1
	s_waitcnt vmcnt(43)
	v_lshlrev_b32_e32 v104, 16, v146
	v_lshlrev_b32_e32 v66, 16, v65
	v_and_b32_e32 v67, 0xffff0000, v65
	v_cmp_gt_u32_e32 vcc, 32, v112
	v_pk_add_f32 v[70:71], v[66:67], 0 op_sel_hi:[1,0]
	v_lshlrev_b32_e32 v68, 16, v69
	v_cndmask_b32_e64 v64, v141, 0, vcc
	v_and_b32_e32 v69, 0xffff0000, v69
	v_pk_mul_f32 v[72:73], v[70:71], s[24:25] op_sel_hi:[1,0]
	v_pk_fma_f32 v[66:67], v[64:65], v[66:67], 0 op_sel_hi:[0,1,0]
	v_pk_fma_f32 v[78:79], v[64:65], v[68:69], v[72:73] op_sel_hi:[0,1,1]
	s_waitcnt vmcnt(41)
	v_mov_b32_e32 v65, v148
	v_mov_b32_e32 v73, v148
	s_nop 1
	v_permlane32_swap_b32_e32 v65, v73
	v_pk_add_f32 v[68:69], v[70:71], v[68:69]
	s_nop 1
	v_and_b32_e32 v190, 31, v112
	v_lshlrev_b32_e32 v70, 16, v65
	v_and_b32_e32 v71, 0xffff0000, v65
	v_pk_add_f32 v[74:75], v[68:69], v[70:71]
	v_pk_mul_f32 v[70:71], v[64:65], v[70:71] op_sel_hi:[0,1]
	v_lshlrev_b32_e32 v72, 16, v73
	v_and_b32_e32 v73, 0xffff0000, v73
	v_pk_fma_f32 v[80:81], v[68:69], s[24:25], v[70:71] op_sel_hi:[1,0,1]
	v_pk_mul_f32 v[68:69], v[74:75], s[24:25] op_sel_hi:[1,0]
	v_ashrrev_i32_e32 v191, 5, v112
	v_pk_fma_f32 v[86:87], v[64:65], v[72:73], v[68:69] op_sel_hi:[0,1,1]
	v_pk_add_f32 v[68:69], v[74:75], v[72:73]
	s_waitcnt vmcnt(35)
	v_mov_b32_e32 v65, v154
	v_mov_b32_e32 v73, v154
	s_nop 1
	v_permlane32_swap_b32_e32 v65, v73
	s_nop 1
	v_exp_f32_e32 v66, v66
	v_lshlrev_b32_e32 v70, 16, v65
	v_and_b32_e32 v71, 0xffff0000, v65
	v_pk_add_f32 v[74:75], v[68:69], v[70:71]
	v_pk_mul_f32 v[70:71], v[64:65], v[70:71] op_sel_hi:[0,1]
	v_lshlrev_b32_e32 v72, 16, v73
	v_and_b32_e32 v73, 0xffff0000, v73
	v_pk_fma_f32 v[88:89], v[68:69], s[24:25], v[70:71] op_sel_hi:[1,0,1]
	v_pk_mul_f32 v[68:69], v[74:75], s[24:25] op_sel_hi:[1,0]
	v_exp_f32_e32 v67, v67
	v_pk_fma_f32 v[98:99], v[64:65], v[72:73], v[68:69] op_sel_hi:[0,1,1]
	v_pk_add_f32 v[68:69], v[74:75], v[72:73]
	s_waitcnt vmcnt(29)
	v_mov_b32_e32 v65, v160
	v_mov_b32_e32 v73, v160
	s_nop 1
	v_permlane32_swap_b32_e32 v65, v73
	s_nop 1
	v_and_b32_e32 v105, 0xffff0000, v146
	v_lshlrev_b32_e32 v70, 16, v65
	v_and_b32_e32 v71, 0xffff0000, v65
	v_pk_add_f32 v[74:75], v[68:69], v[70:71]
	v_pk_mul_f32 v[70:71], v[64:65], v[70:71] op_sel_hi:[0,1]
	v_lshlrev_b32_e32 v72, 16, v73
	v_and_b32_e32 v73, 0xffff0000, v73
	v_pk_fma_f32 v[94:95], v[68:69], s[24:25], v[70:71] op_sel_hi:[1,0,1]
	v_pk_mul_f32 v[68:69], v[74:75], s[24:25] op_sel_hi:[1,0]
	v_exp_f32_e32 v80, v80
	v_pk_fma_f32 v[96:97], v[64:65], v[72:73], v[68:69] op_sel_hi:[0,1,1]
	v_pk_add_f32 v[68:69], v[74:75], v[72:73]
	s_waitcnt vmcnt(23)
	v_mov_b32_e32 v65, v166
	v_mov_b32_e32 v73, v166
	s_nop 1
	v_permlane32_swap_b32_e32 v65, v73
	s_nop 1
	v_exp_f32_e32 v81, v81
	v_lshlrev_b32_e32 v70, 16, v65
	v_and_b32_e32 v71, 0xffff0000, v65
	v_pk_add_f32 v[74:75], v[68:69], v[70:71]
	v_pk_mul_f32 v[70:71], v[64:65], v[70:71] op_sel_hi:[0,1]
	v_lshlrev_b32_e32 v72, 16, v73
	v_and_b32_e32 v73, 0xffff0000, v73
	v_pk_fma_f32 v[90:91], v[68:69], s[24:25], v[70:71] op_sel_hi:[1,0,1]
	v_pk_mul_f32 v[68:69], v[74:75], s[24:25] op_sel_hi:[1,0]
	v_exp_f32_e32 v88, v88
	v_pk_fma_f32 v[92:93], v[64:65], v[72:73], v[68:69] op_sel_hi:[0,1,1]
	v_pk_add_f32 v[68:69], v[74:75], v[72:73]
	s_waitcnt vmcnt(17)
	v_mov_b32_e32 v65, v172
	v_mov_b32_e32 v73, v172
	s_nop 1
	v_permlane32_swap_b32_e32 v65, v73
	s_nop 1
	v_exp_f32_e32 v89, v89
	v_lshlrev_b32_e32 v70, 16, v65
	v_and_b32_e32 v71, 0xffff0000, v65
	v_pk_add_f32 v[74:75], v[68:69], v[70:71]
	v_pk_mul_f32 v[70:71], v[64:65], v[70:71] op_sel_hi:[0,1]
	v_lshlrev_b32_e32 v72, 16, v73
	v_and_b32_e32 v73, 0xffff0000, v73
	v_pk_fma_f32 v[82:83], v[68:69], s[24:25], v[70:71] op_sel_hi:[1,0,1]
	v_pk_mul_f32 v[68:69], v[74:75], s[24:25] op_sel_hi:[1,0]
	v_exp_f32_e32 v96, v96
	v_pk_fma_f32 v[84:85], v[64:65], v[72:73], v[68:69] op_sel_hi:[0,1,1]
	v_pk_add_f32 v[68:69], v[74:75], v[72:73]
	s_waitcnt vmcnt(11)
	v_mov_b32_e32 v65, v178
	v_mov_b32_e32 v73, v178
	s_nop 1
	v_permlane32_swap_b32_e32 v65, v73
	s_nop 1
	v_exp_f32_e32 v97, v97
	v_lshlrev_b32_e32 v70, 16, v65
	v_and_b32_e32 v71, 0xffff0000, v65
	v_pk_add_f32 v[100:101], v[68:69], v[70:71]
	v_pk_mul_f32 v[70:71], v[64:65], v[70:71] op_sel_hi:[0,1]
	v_lshlrev_b32_e32 v72, 16, v73
	v_and_b32_e32 v73, 0xffff0000, v73
	v_pk_fma_f32 v[74:75], v[68:69], s[24:25], v[70:71] op_sel_hi:[1,0,1]
	v_pk_mul_f32 v[68:69], v[100:101], s[24:25] op_sel_hi:[1,0]
	v_exp_f32_e32 v94, v94
	v_pk_fma_f32 v[76:77], v[64:65], v[72:73], v[68:69] op_sel_hi:[0,1,1]
	v_pk_add_f32 v[68:69], v[100:101], v[72:73]
	s_waitcnt vmcnt(5)
	v_mov_b32_e32 v65, v184
	v_mov_b32_e32 v72, v184
	s_nop 1
	v_permlane32_swap_b32_e32 v65, v72
	s_nop 1
	v_exp_f32_e32 v95, v95
	v_lshlrev_b32_e32 v70, 16, v65
	v_and_b32_e32 v71, 0xffff0000, v65
	v_pk_add_f32 v[102:103], v[68:69], v[70:71]
	v_pk_mul_f32 v[70:71], v[64:65], v[70:71] op_sel_hi:[0,1]
	v_lshlrev_b32_e32 v100, 16, v72
	v_and_b32_e32 v101, 0xffff0000, v72
	v_pk_fma_f32 v[70:71], v[68:69], s[24:25], v[70:71] op_sel_hi:[1,0,1]
	v_pk_mul_f32 v[68:69], v[102:103], s[24:25] op_sel_hi:[1,0]
	v_exp_f32_e32 v92, v92
	v_pk_fma_f32 v[72:73], v[64:65], v[100:101], v[68:69] op_sel_hi:[0,1,1]
	v_pk_add_f32 v[64:65], v[102:103], v[100:101]
	v_lshl_add_u32 v68, v190, 3, s42
	v_mul_f32_e32 v64, 0x3fb8aa3b, v64
	v_mul_f32_e32 v65, 0x3fb8aa3b, v65
	v_exp_f32_e32 v64, v64
	v_exp_f32_e32 v65, v65
	v_lshlrev_b32_e32 v69, 2, v190
	v_lshlrev_b32_e32 v100, 16, v143
	v_and_b32_e32 v101, 0xffff0000, v143
	s_barrier
; #define LAS __attribute__((address_space(3)))
; __device__ __forceinline__ unsigned cvt_pk_bf16(float lo, float hi) { unsigned r; asm volatile("v_cvt_pk_bf16_f32 %0, %1, %2" : "=v"(r) : "v"(lo), "v"(hi)); return r; }
; #define RAW2(w) ((f32x2){__uint_as_float((w) << 16), __uint_as_float((w) & 0xffff0000u)})
; template <int role> __device__ __forceinline__ void ph_scan1m_r(Ctx& C) {
;     ...
;             *(LAS f32x2*)(gT + c0) = GT2;
;             float bgx[8], bgy[8], kgx[8], kgy[8];
;             { LAS bf16* wKR = imKR + par * 72 + c0; LAS bf16* wBK = imBK + (8 * par) * 72 + c0;
; #pragma unroll
;               for (int j = 0; j < 8; ++j) {
;                   const f32x2 eL = (f32x2){__builtin_amdgcn_exp2f(Lt[j].x), __builtin_amdgcn_exp2f(Lt[j].y)}, eLm = (f32x2){__builtin_amdgcn_exp2f(Lm[j].x), __builtin_amdgcn_exp2f(Lm[j].y)};
;                   const f32x2 ie = (f32x2){__builtin_amdgcn_rcpf(eL.x), __builtin_amdgcn_rcpf(eL.y)};
;                   const f32x2 nk = RAW2(rn[j]), a_ = RAW2(ra[j]), rr = RAW2(rr_[j]);
;                   const f32x2 b_ = -nk * a_;
;                   const f32x2 kkh = nk * eLm, rh = rr * eL, bt = b_ * ie, bgf = bt * GT2;
;                   *(LAS unsigned*)(wKR + (2 * j) * 72) = pg8::cvt_pk_bf16(kkh.x, kkh.y); *(LAS unsigned*)(wKR + (16 + 2 * j) * 72) = pg8::cvt_pk_bf16(rh.x, rh.y);
;                   *(LAS unsigned*)(wBK + j * 72) = pg8::cvt_pk_bf16(bt.x, bt.y);
;                   f32x2 kgf = (f32x2){0.f, 0.f};
;                   if (role) { const f32x2 kr = RAW2(rk[j]); const f32x2 kd = kr * (a_ * ka2 + k1), kt_ = kd * ie; kgf = kt_ * GT2; *(LAS unsigned*)(wBK + (16 + j) * 72) = pg8::cvt_pk_bf16(kt_.x, kt_.y); }
;                   bgx[j] = bgf.x; bgy[j] = bgf.y; if (role) { kgx[j] = kgf.x; kgy[j] = kgf.y; } } }
	ds_write_b64 v68, v[64:65] offset:14336
	v_mul_lo_u32 v68, v191, s61
	v_add3_u32 v108, s42, v68, v69
	v_mul_lo_u32 v68, v191, s62
	v_add3_u32 v109, s42, v68, v69
	v_exp_f32_e32 v68, v78
	v_exp_f32_e32 v69, v79
	v_pk_mul_f32 v[66:67], v[66:67], v[100:101]
	v_lshlrev_b32_e32 v102, 16, v144
	v_rcp_f32_e32 v78, v68
	v_rcp_f32_e32 v79, v69
	v_and_b32_e32 v103, 0xffff0000, v144
	v_cvt_pk_bf16_f32 v66, v66, v67
	v_pk_mul_f32 v[106:107], v[102:103], v[100:101] neg_lo:[0,1] neg_hi:[0,1]
	v_pk_mul_f32 v[100:101], v[68:69], v[104:105]
	ds_write_b32 v108, v66
	v_cvt_pk_bf16_f32 v66, v100, v101
	v_pk_mul_f32 v[104:105], v[106:107], v[78:79]
	ds_write_b32 v108, v66 offset:2304
	v_cvt_pk_bf16_f32 v66, v104, v105
	ds_write_b32 v109, v66 offset:4608
	v_lshlrev_b32_e32 v66, 16, v145
	v_and_b32_e32 v67, 0xffff0000, v145
	v_pk_fma_f32 v[100:101], v[116:117], v[102:103], v[118:119]
	v_pk_mul_f32 v[68:69], v[104:105], v[64:65]
	v_pk_mul_f32 v[66:67], v[100:101], v[66:67]
	v_lshlrev_b32_e32 v100, 16, v149
	v_pk_mul_f32 v[78:79], v[66:67], v[78:79]
	v_and_b32_e32 v101, 0xffff0000, v149
	v_pk_mul_f32 v[66:67], v[78:79], v[64:65]
	v_cvt_pk_bf16_f32 v78, v78, v79
	ds_write_b32 v109, v78 offset:6912
	v_exp_f32_e32 v78, v86
	v_exp_f32_e32 v79, v87
	v_lshlrev_b32_e32 v102, 16, v150
	v_and_b32_e32 v103, 0xffff0000, v150
	v_rcp_f32_e32 v86, v78
	v_rcp_f32_e32 v87, v79
	v_lshlrev_b32_e32 v104, 16, v152
	v_and_b32_e32 v105, 0xffff0000, v152
	v_pk_mul_f32 v[106:107], v[102:103], v[100:101] neg_lo:[0,1] neg_hi:[0,1]
	v_pk_mul_f32 v[100:101], v[80:81], v[100:101]
	v_pk_mul_f32 v[78:79], v[78:79], v[104:105]
	v_cvt_pk_bf16_f32 v100, v100, v101
	ds_write_b32 v108, v100 offset:288
	v_cvt_pk_bf16_f32 v78, v78, v79
	v_pk_mul_f32 v[104:105], v[106:107], v[86:87]
	ds_write_b32 v108, v78 offset:2592
	v_cvt_pk_bf16_f32 v78, v104, v105
	ds_write_b32 v109, v78 offset:4752
	v_lshlrev_b32_e32 v78, 16, v151
	v_and_b32_e32 v79, 0xffff0000, v151
	v_pk_fma_f32 v[100:101], v[116:117], v[102:103], v[118:119]
	v_pk_mul_f32 v[80:81], v[104:105], v[64:65]
	v_pk_mul_f32 v[78:79], v[100:101], v[78:79]
	v_lshlrev_b32_e32 v100, 16, v155
	v_pk_mul_f32 v[86:87], v[78:79], v[86:87]
	v_and_b32_e32 v101, 0xffff0000, v155
	v_pk_mul_f32 v[78:79], v[86:87], v[64:65]
	v_cvt_pk_bf16_f32 v86, v86, v87
	ds_write_b32 v109, v86 offset:7056
	v_exp_f32_e32 v86, v98
	v_exp_f32_e32 v87, v99
	v_lshlrev_b32_e32 v102, 16, v156
	v_and_b32_e32 v103, 0xffff0000, v156
	v_rcp_f32_e32 v98, v86
	v_rcp_f32_e32 v99, v87
	v_lshlrev_b32_e32 v104, 16, v158
	v_and_b32_e32 v105, 0xffff0000, v158
	v_pk_mul_f32 v[106:107], v[102:103], v[100:101] neg_lo:[0,1] neg_hi:[0,1]
	v_pk_mul_f32 v[100:101], v[88:89], v[100:101]
	v_pk_mul_f32 v[86:87], v[86:87], v[104:105]
	v_cvt_pk_bf16_f32 v100, v100, v101
	ds_write_b32 v108, v100 offset:576
	v_cvt_pk_bf16_f32 v86, v86, v87
	v_pk_mul_f32 v[104:105], v[106:107], v[98:99]
	ds_write_b32 v108, v86 offset:2880
	v_cvt_pk_bf16_f32 v86, v104, v105
	ds_write_b32 v109, v86 offset:4896
	v_lshlrev_b32_e32 v86, 16, v157
	v_and_b32_e32 v87, 0xffff0000, v157
	v_pk_fma_f32 v[100:101], v[116:117], v[102:103], v[118:119]
	v_pk_mul_f32 v[88:89], v[104:105], v[64:65]
	v_pk_mul_f32 v[86:87], v[100:101], v[86:87]
	v_lshlrev_b32_e32 v100, 16, v161
	v_pk_mul_f32 v[98:99], v[86:87], v[98:99]
	v_and_b32_e32 v101, 0xffff0000, v161
	v_pk_mul_f32 v[86:87], v[98:99], v[64:65]
	v_cvt_pk_bf16_f32 v98, v98, v99
	ds_write_b32 v109, v98 offset:7200
	v_rcp_f32_e32 v98, v96
	v_rcp_f32_e32 v99, v97
	v_pk_mul_f32 v[94:95], v[94:95], v[100:101]
	v_lshlrev_b32_e32 v102, 16, v162
	v_and_b32_e32 v103, 0xffff0000, v162
	v_lshlrev_b32_e32 v104, 16, v164
	v_and_b32_e32 v105, 0xffff0000, v164
	v_cvt_pk_bf16_f32 v94, v94, v95
	v_pk_mul_f32 v[106:107], v[102:103], v[100:101] neg_lo:[0,1] neg_hi:[0,1]
	v_pk_mul_f32 v[100:101], v[96:97], v[104:105]
	ds_write_b32 v108, v94 offset:864
	v_cvt_pk_bf16_f32 v94, v100, v101
	v_pk_mul_f32 v[104:105], v[106:107], v[98:99]
	ds_write_b32 v108, v94 offset:3168
	v_cvt_pk_bf16_f32 v94, v104, v105
	ds_write_b32 v109, v94 offset:5040
	v_lshlrev_b32_e32 v94, 16, v163
	v_and_b32_e32 v95, 0xffff0000, v163
	v_pk_fma_f32 v[100:101], v[116:117], v[102:103], v[118:119]
	v_exp_f32_e32 v93, v93
	v_pk_mul_f32 v[94:95], v[100:101], v[94:95]
	v_exp_f32_e32 v90, v90
	v_exp_f32_e32 v91, v91
	v_pk_mul_f32 v[98:99], v[94:95], v[98:99]
	v_lshlrev_b32_e32 v100, 16, v167
	v_pk_mul_f32 v[94:95], v[98:99], v[64:65]
	v_cvt_pk_bf16_f32 v98, v98, v99
	ds_write_b32 v109, v98 offset:7344
	v_rcp_f32_e32 v98, v92
	v_rcp_f32_e32 v99, v93
	v_and_b32_e32 v101, 0xffff0000, v167
	v_pk_mul_f32 v[90:91], v[90:91], v[100:101]
	v_pk_mul_f32 v[96:97], v[104:105], v[64:65]
	v_lshlrev_b32_e32 v102, 16, v168
	v_and_b32_e32 v103, 0xffff0000, v168
	v_lshlrev_b32_e32 v104, 16, v170
	v_and_b32_e32 v105, 0xffff0000, v170
	v_cvt_pk_bf16_f32 v90, v90, v91
	v_pk_mul_f32 v[106:107], v[102:103], v[100:101] neg_lo:[0,1] neg_hi:[0,1]
	v_pk_mul_f32 v[92:93], v[92:93], v[104:105]
	ds_write_b32 v108, v90 offset:1152
	v_cvt_pk_bf16_f32 v90, v92, v93
	v_pk_mul_f32 v[100:101], v[106:107], v[98:99]
	ds_write_b32 v108, v90 offset:3456
	v_cvt_pk_bf16_f32 v90, v100, v101
	ds_write_b32 v109, v90 offset:5184
	v_lshlrev_b32_e32 v90, 16, v169
	v_and_b32_e32 v91, 0xffff0000, v169
	v_pk_fma_f32 v[92:93], v[116:117], v[102:103], v[118:119]
	v_exp_f32_e32 v84, v84
	v_exp_f32_e32 v85, v85
	v_pk_mul_f32 v[90:91], v[92:93], v[90:91]
	v_exp_f32_e32 v82, v82
	v_exp_f32_e32 v83, v83
	v_pk_mul_f32 v[90:91], v[90:91], v[98:99]
	v_lshlrev_b32_e32 v98, 16, v173
	v_pk_mul_f32 v[92:93], v[90:91], v[64:65]
	v_cvt_pk_bf16_f32 v90, v90, v91
	ds_write_b32 v109, v90 offset:7488
	v_rcp_f32_e32 v90, v84
; #define LAS __attribute__((address_space(3)))
; __device__ __forceinline__ unsigned cvt_pk_bf16(float lo, float hi) { unsigned r; asm volatile("v_cvt_pk_bf16_f32 %0, %1, %2" : "=v"(r) : "v"(lo), "v"(hi)); return r; }
; template <int role> __device__ __forceinline__ void ph_scan1m_r(Ctx& C) {
;     ...
;                   bgx[j] = bgf.x; bgy[j] = bgf.y; if (role) { kgx[j] = kgf.x; kgy[j] = kgf.y; } } }
;             { u32x4 w0, w1;
; #pragma unroll
;               for (int q = 0; q < 4; ++q) { w0[q] = pg8::cvt_pk_bf16(bgx[2 * q], bgx[2 * q + 1]); w1[q] = pg8::cvt_pk_bf16(bgy[2 * q], bgy[2 * q + 1]); }
;               *(LAS u32x4*)(imBGT + c0 * 40 + 8 * par) = w0; *(LAS u32x4*)(imBGT + (c0 + 1) * 40 + 8 * par) = w1;
;               if (role) {
; #pragma unroll
;                   for (int q = 0; q < 4; ++q) { w0[q] = pg8::cvt_pk_bf16(kgx[2 * q], kgx[2 * q + 1]); w1[q] = pg8::cvt_pk_bf16(kgy[2 * q], kgy[2 * q + 1]); }
;                   *(LAS u32x4*)(imBGT + c0 * 40 + 16 + 8 * par) = w0; *(LAS u32x4*)(imBGT + (c0 + 1) * 40 + 16 + 8 * par) = w1;
; #pragma unroll
;                   for (int q = 0; q < 4; ++q) { w0[q] = __builtin_amdgcn_perm(rv[2 * q + 1], rv[2 * q], 0x05040100u); w1[q] = __builtin_amdgcn_perm(rv[2 * q + 1], rv[2 * q], 0x07060302u); }
;                   *(LAS u32x4*)(imVT + c0 * 24 + 8 * par) = w0; *(LAS u32x4*)(imVT + (c0 + 1) * 24 + 8 * par) = w1; } }
;             asm volatile("s_waitcnt lgkmcnt(0)" ::: "memory");
	v_rcp_f32_e32 v91, v85
	v_and_b32_e32 v99, 0xffff0000, v173
	v_pk_mul_f32 v[82:83], v[82:83], v[98:99]
	v_pk_mul_f32 v[104:105], v[100:101], v[64:65]
	v_lshlrev_b32_e32 v100, 16, v174
	v_and_b32_e32 v101, 0xffff0000, v174
	v_lshlrev_b32_e32 v102, 16, v176
	v_and_b32_e32 v103, 0xffff0000, v176
	v_cvt_pk_bf16_f32 v82, v82, v83
	v_pk_mul_f32 v[106:107], v[100:101], v[98:99] neg_lo:[0,1] neg_hi:[0,1]
	v_pk_mul_f32 v[84:85], v[84:85], v[102:103]
	ds_write_b32 v108, v82 offset:1440
	v_cvt_pk_bf16_f32 v82, v84, v85
	v_pk_mul_f32 v[98:99], v[106:107], v[90:91]
	ds_write_b32 v108, v82 offset:3744
	v_cvt_pk_bf16_f32 v82, v98, v99
	ds_write_b32 v109, v82 offset:5328
	v_lshlrev_b32_e32 v82, 16, v175
	v_and_b32_e32 v83, 0xffff0000, v175
	v_pk_fma_f32 v[84:85], v[116:117], v[100:101], v[118:119]
	v_exp_f32_e32 v76, v76
	v_exp_f32_e32 v77, v77
	v_pk_mul_f32 v[82:83], v[84:85], v[82:83]
	v_exp_f32_e32 v74, v74
	v_exp_f32_e32 v75, v75
	v_pk_mul_f32 v[82:83], v[82:83], v[90:91]
	v_lshlrev_b32_e32 v90, 16, v179
	v_pk_mul_f32 v[84:85], v[82:83], v[64:65]
	v_cvt_pk_bf16_f32 v82, v82, v83
	ds_write_b32 v109, v82 offset:7632
	v_rcp_f32_e32 v82, v76
	v_rcp_f32_e32 v83, v77
	v_and_b32_e32 v91, 0xffff0000, v179
	v_pk_mul_f32 v[74:75], v[74:75], v[90:91]
	v_pk_mul_f32 v[102:103], v[98:99], v[64:65]
	v_lshlrev_b32_e32 v98, 16, v180
	v_and_b32_e32 v99, 0xffff0000, v180
	v_lshlrev_b32_e32 v100, 16, v182
	v_and_b32_e32 v101, 0xffff0000, v182
	v_cvt_pk_bf16_f32 v74, v74, v75
	v_pk_mul_f32 v[106:107], v[98:99], v[90:91] neg_lo:[0,1] neg_hi:[0,1]
	v_pk_mul_f32 v[76:77], v[76:77], v[100:101]
	ds_write_b32 v108, v74 offset:1728
	v_cvt_pk_bf16_f32 v74, v76, v77
	v_pk_mul_f32 v[90:91], v[106:107], v[82:83]
	ds_write_b32 v108, v74 offset:4032
	v_cvt_pk_bf16_f32 v74, v90, v91
	ds_write_b32 v109, v74 offset:5472
	v_lshlrev_b32_e32 v74, 16, v181
	v_and_b32_e32 v75, 0xffff0000, v181
	v_pk_fma_f32 v[76:77], v[116:117], v[98:99], v[118:119]
	v_exp_f32_e32 v72, v72
	v_exp_f32_e32 v73, v73
	v_pk_mul_f32 v[74:75], v[76:77], v[74:75]
	v_exp_f32_e32 v70, v70
	v_exp_f32_e32 v71, v71
	v_pk_mul_f32 v[74:75], v[74:75], v[82:83]
	s_waitcnt vmcnt(4)
	v_lshlrev_b32_e32 v82, 16, v185
	v_pk_mul_f32 v[76:77], v[64:65], v[74:75]
	v_cvt_pk_bf16_f32 v74, v74, v75
	ds_write_b32 v109, v74 offset:7776
	v_rcp_f32_e32 v74, v72
	v_rcp_f32_e32 v75, v73
	v_and_b32_e32 v83, 0xffff0000, v185
	v_pk_mul_f32 v[70:71], v[70:71], v[82:83]
	v_pk_mul_f32 v[100:101], v[64:65], v[90:91]
	s_waitcnt vmcnt(3)
	v_lshlrev_b32_e32 v90, 16, v186
	v_and_b32_e32 v91, 0xffff0000, v186
	s_waitcnt vmcnt(1)
	v_lshlrev_b32_e32 v98, 16, v188
	v_and_b32_e32 v99, 0xffff0000, v188
	v_cvt_pk_bf16_f32 v70, v70, v71
	v_pk_mul_f32 v[106:107], v[90:91], v[82:83] neg_lo:[0,1] neg_hi:[0,1]
	v_pk_mul_f32 v[72:73], v[72:73], v[98:99]
	ds_write_b32 v108, v70 offset:2016
	v_cvt_pk_bf16_f32 v70, v72, v73
	v_pk_mul_f32 v[82:83], v[106:107], v[74:75]
	ds_write_b32 v108, v70 offset:4320
	v_cvt_pk_bf16_f32 v70, v82, v83
	ds_write_b32 v109, v70 offset:5616
	v_lshlrev_b32_e32 v70, 16, v187
	v_and_b32_e32 v71, 0xffff0000, v187
	v_pk_fma_f32 v[72:73], v[116:117], v[90:91], v[118:119]
	v_pk_mul_f32 v[98:99], v[64:65], v[82:83]
	v_pk_mul_f32 v[70:71], v[72:73], v[70:71]
	s_add_i32 s79, s22, s72
	v_pk_mul_f32 v[70:71], v[70:71], v[74:75]
	s_add_i32 s2, s75, 16
	v_pk_mul_f32 v[82:83], v[64:65], v[70:71]
	v_cvt_pk_bf16_f32 v64, v70, v71
	ds_write_b32 v109, v64 offset:7920
	v_cvt_pk_bf16_f32 v68, v68, v80
	v_cvt_pk_bf16_f32 v72, v69, v81
	v_cvt_pk_bf16_f32 v69, v88, v96
	v_cvt_pk_bf16_f32 v73, v89, v97
	v_cvt_pk_bf16_f32 v70, v104, v102
	v_lshlrev_b32_e32 v104, 4, v191
	v_add_u32_e32 v192, s42, v104
	v_lshl_or_b32 v81, v190, 1, 1
	v_mad_u32_u24 v80, v190, s63, v192
	v_mad_u32_u24 v88, v81, s64, v192
	v_cvt_pk_bf16_f32 v74, v105, v103
	v_cvt_pk_bf16_f32 v71, v100, v98
	v_cvt_pk_bf16_f32 v75, v101, v99
	ds_write_b128 v80, v[68:71] offset:9216
	ds_write_b128 v88, v[72:75] offset:9216
	v_cvt_pk_bf16_f32 v64, v66, v78
	v_cvt_pk_bf16_f32 v68, v67, v79
	v_cvt_pk_bf16_f32 v65, v86, v94
	v_cvt_pk_bf16_f32 v69, v87, v95
	v_cvt_pk_bf16_f32 v66, v92, v84
	v_cvt_pk_bf16_f32 v70, v93, v85
	v_cvt_pk_bf16_f32 v67, v76, v82
	v_cvt_pk_bf16_f32 v71, v77, v83
	ds_write_b128 v80, v[64:67] offset:9248
	ds_write_b128 v88, v[68:71] offset:9248
	v_perm_b32 v64, v153, v147, s65
	v_perm_b32 v65, v165, v159, s65
	v_perm_b32 v66, v177, v171, s65
	s_waitcnt vmcnt(0)
	v_perm_b32 v67, v189, v183, s65
	v_mad_u32_u24 v72, v190, s67, v192
	v_perm_b32 v68, v153, v147, s66
	v_perm_b32 v69, v165, v159, s66
	v_perm_b32 v70, v177, v171, s66
	v_perm_b32 v71, v189, v183, s66
	ds_write_b128 v72, v[64:67] offset:14592
	v_mad_u32_u24 v64, v81, 48, v192
	ds_write_b128 v64, v[68:71] offset:14592
	s_waitcnt lgkmcnt(0)
	s_and_b64 s[0:1], s[30:31], exec
	s_cselect_b32 s38, s79, s2
	v_lshlrev_b32_e32 v193, 3, v191
	s_cmpk_eq_i32 s72, 0x1f0
	s_cbranch_scc1 .Lsc1_r1_noload
	s_add_i32 s79, s79, 16
	s_and_b64 s[0:1], s[30:31], exec
	s_cselect_b32 s0, s79, s75
	s_ashr_i32 s1, s0, 31
	s_lshl_b64 s[0:1], s[0:1], 11
	s_or_b32 s0, s0, s78
	s_add_u32 s2, s27, s0
	s_addc_u32 s3, s29, s1
	s_add_u32 s4, s40, s0
	s_addc_u32 s5, s41, s1
	s_add_u32 s6, s70, s0
	s_addc_u32 s7, s71, s1
	s_add_u32 s8, s47, s0
	s_addc_u32 s9, s49, s1
	v_mov_b32_e32 v232, v140
	s_add_u32 s10, s43, s0
	s_addc_u32 s11, s44, s1
	v_ashrrev_i32_e32 v246, 5, v232
	v_ashrrev_i32_e32 v233, 31, v246
	v_lshlrev_b32_e32 v232, 1, v232
	s_add_u32 s12, s45, s0
	v_mov_b64_e32 v[244:245], s[36:37]
	v_and_b32_e32 v252, 62, v232
	s_addc_u32 s13, s46, s1
	v_mul_lo_u32 v247, s34, v233
	v_mul_lo_u32 v248, s35, v246
	v_mad_u64_u32 v[232:233], s[0:1], s34, v246, 0
	v_mad_u64_u32 v[244:245], s[0:1], s34, v246, v[244:245]
	v_add3_u32 v233, v233, v247, v248
	v_or_b32_e32 v232, v232, v252
	v_add3_u32 v245, v248, v245, v247
	v_lshlrev_b64 v[232:233], 1, v[232:233]
	v_or_b32_e32 v246, v244, v252
	v_mov_b32_e32 v247, v245
	v_lshl_add_u64 v[234:235], s[2:3], 0, v[232:233]
	v_lshl_add_u64 v[240:241], s[8:9], 0, v[232:233]
	v_lshlrev_b64 v[246:247], 1, v[246:247]
	v_lshl_add_u64 v[236:237], s[4:5], 0, v[232:233]
	v_lshl_add_u64 v[238:239], s[6:7], 0, v[232:233]
	v_lshl_add_u64 v[242:243], s[10:11], 0, v[232:233]
	v_lshl_add_u64 v[232:233], s[12:13], 0, v[232:233]
	v_lshl_add_u64 v[248:249], s[2:3], 0, v[246:247]
	v_lshl_add_u64 v[250:251], s[4:5], 0, v[246:247]
	global_load_dword v142, v[234:235], off
	global_load_dword v143, v[236:237], off
	global_load_dword v144, v[238:239], off
	global_load_dword v145, v[240:241], off
	global_load_dword v146, v[242:243], off
	global_load_dword v147, v[232:233], off
	global_load_dword v148, v[248:249], off
	global_load_dword v149, v[250:251], off
	v_lshl_add_u64 v[240:241], v[244:245], 0, s[36:37]
	v_or_b32_e32 v242, v240, v252
	v_mov_b32_e32 v243, v241
	v_lshl_add_u64 v[232:233], s[6:7], 0, v[246:247]
	v_lshl_add_u64 v[236:237], s[10:11], 0, v[246:247]
	v_lshlrev_b64 v[242:243], 1, v[242:243]
	v_lshl_add_u64 v[234:235], s[8:9], 0, v[246:247]
	v_lshl_add_u64 v[238:239], s[12:13], 0, v[246:247]
	v_lshl_add_u64 v[244:245], s[2:3], 0, v[242:243]
	v_lshl_add_u64 v[246:247], s[4:5], 0, v[242:243]
	v_lshl_add_u64 v[248:249], s[6:7], 0, v[242:243]
	v_lshl_add_u64 v[250:251], s[8:9], 0, v[242:243]
	global_load_dword v150, v[232:233], off
	global_load_dword v151, v[234:235], off
	global_load_dword v152, v[236:237], off
	global_load_dword v153, v[238:239], off
	global_load_dword v154, v[244:245], off
	global_load_dword v155, v[246:247], off
	global_load_dword v156, v[248:249], off
	global_load_dword v157, v[250:251], off
	v_lshl_add_u64 v[236:237], v[240:241], 0, s[36:37]
	v_or_b32_e32 v238, v236, v252
	v_mov_b32_e32 v239, v237
	v_lshl_add_u64 v[232:233], s[10:11], 0, v[242:243]
	v_lshlrev_b64 v[238:239], 1, v[238:239]
	v_lshl_add_u64 v[234:235], s[12:13], 0, v[242:243]
	v_lshl_add_u64 v[240:241], s[2:3], 0, v[238:239]
	v_lshl_add_u64 v[242:243], s[4:5], 0, v[238:239]
	v_lshl_add_u64 v[244:245], s[6:7], 0, v[238:239]
	v_lshl_add_u64 v[246:247], s[8:9], 0, v[238:239]
	v_lshl_add_u64 v[248:249], s[10:11], 0, v[238:239]
	v_lshl_add_u64 v[238:239], s[12:13], 0, v[238:239]
	global_load_dword v158, v[232:233], off
	global_load_dword v159, v[234:235], off
	global_load_dword v160, v[240:241], off
	global_load_dword v161, v[242:243], off
	global_load_dword v162, v[244:245], off
	global_load_dword v163, v[246:247], off
	global_load_dword v164, v[248:249], off
	global_load_dword v165, v[238:239], off
	v_lshl_add_u64 v[232:233], v[236:237], 0, s[36:37]
	v_or_b32_e32 v234, v232, v252
	v_mov_b32_e32 v235, v233
	v_lshl_add_u64 v[232:233], v[232:233], 0, s[36:37]
	v_lshlrev_b64 v[234:235], 1, v[234:235]
	v_or_b32_e32 v246, v232, v252
	v_mov_b32_e32 v247, v233
	v_lshl_add_u64 v[236:237], s[2:3], 0, v[234:235]
	v_lshl_add_u64 v[242:243], s[8:9], 0, v[234:235]
	v_lshlrev_b64 v[246:247], 1, v[246:247]
	v_lshl_add_u64 v[232:233], v[232:233], 0, s[36:37]
	v_lshl_add_u64 v[238:239], s[4:5], 0, v[234:235]
	v_lshl_add_u64 v[240:241], s[6:7], 0, v[234:235]
	v_lshl_add_u64 v[244:245], s[10:11], 0, v[234:235]
	v_lshl_add_u64 v[234:235], s[12:13], 0, v[234:235]
	v_lshl_add_u64 v[248:249], s[2:3], 0, v[246:247]
	v_lshl_add_u64 v[250:251], s[4:5], 0, v[246:247]
	global_load_dword v166, v[236:237], off
	global_load_dword v167, v[238:239], off
	global_load_dword v168, v[240:241], off
	global_load_dword v169, v[242:243], off
	global_load_dword v170, v[244:245], off
	global_load_dword v171, v[234:235], off
	global_load_dword v172, v[248:249], off
	global_load_dword v173, v[250:251], off
	v_or_b32_e32 v242, v232, v252
	v_mov_b32_e32 v243, v233
	v_lshl_add_u64 v[232:233], v[232:233], 0, s[36:37]
	v_lshl_add_u64 v[234:235], s[6:7], 0, v[246:247]
	v_lshlrev_b64 v[242:243], 1, v[242:243]
	v_or_b32_e32 v232, v232, v252
	v_lshl_add_u64 v[236:237], s[8:9], 0, v[246:247]
	v_lshl_add_u64 v[238:239], s[10:11], 0, v[246:247]
	v_lshl_add_u64 v[240:241], s[12:13], 0, v[246:247]
	v_lshl_add_u64 v[244:245], s[2:3], 0, v[242:243]
	v_lshl_add_u64 v[246:247], s[4:5], 0, v[242:243]
	v_lshl_add_u64 v[248:249], s[6:7], 0, v[242:243]
	v_lshl_add_u64 v[250:251], s[8:9], 0, v[242:243]
	global_load_dword v174, v[234:235], off
	global_load_dword v175, v[236:237], off
	global_load_dword v176, v[238:239], off
	global_load_dword v177, v[240:241], off
	global_load_dword v178, v[244:245], off
	global_load_dword v179, v[246:247], off
	global_load_dword v180, v[248:249], off
	global_load_dword v181, v[250:251], off
	v_lshl_add_u64 v[234:235], s[10:11], 0, v[242:243]
	v_lshlrev_b64 v[232:233], 1, v[232:233]
	v_lshl_add_u64 v[236:237], s[12:13], 0, v[242:243]
	v_lshl_add_u64 v[238:239], s[2:3], 0, v[232:233]
	v_lshl_add_u64 v[240:241], s[4:5], 0, v[232:233]
	v_lshl_add_u64 v[242:243], s[6:7], 0, v[232:233]
	v_lshl_add_u64 v[244:245], s[8:9], 0, v[232:233]
	v_lshl_add_u64 v[246:247], s[10:11], 0, v[232:233]
	v_lshl_add_u64 v[232:233], s[12:13], 0, v[232:233]
	global_load_dword v182, v[234:235], off
	global_load_dword v183, v[236:237], off
	global_load_dword v184, v[238:239], off
	global_load_dword v185, v[240:241], off
	global_load_dword v186, v[242:243], off
	global_load_dword v187, v[244:245], off
	global_load_dword v188, v[246:247], off
	global_load_dword v189, v[232:233], off
; #define LAS __attribute__((address_space(3)))
; template <int role> __device__ __forceinline__ void ph_scan1m_r(Ctx& C) {
;     ...
;             { f32x16 m;
; #pragma unroll
;               for (int e = 0; e < 16; ++e) m[e] = 0.f;
; #pragma unroll
;               for (int ks = 0; ks < 4; ++ks) { const bf16x8 af = *(const LAS bf16x8*)(imBK + r31 * 72 + 16 * ks + 8 * hh), bfr = *(const LAS bf16x8*)(imKR + r31 * 72 + 16 * ks + 8 * hh); m = __builtin_amdgcn_mfma_f32_32x32x16_bf16(af, bfr, m, 0, 0, 0); }
;               asm volatile("s_waitcnt lgkmcnt(0)" ::: "memory");
;               const int tq = r31 & 15; const bool ycol = r31 >= 16;
; #pragma unroll
;               for (int g = 0; g < 4; ++g) { f32x4 o;
; #pragma unroll
;                   for (int e = 0; e < 4; ++e) { const int sq = 2 * (4 * hh + e) + (g & 1); const bool ok = ycol ? (sq <= tq) : (sq < tq); o[e] = ok ? m[4 * g + e] : 0.f; }
;                   *(LAS f32x4*)(MT + r31 * 36 + 8 * g + 4 * hh) = o; } }
;             asm volatile("s_waitcnt lgkmcnt(0)" ::: "memory");
;             __builtin_amdgcn_sched_barrier(0);
;             f32x16 ya[2];
; #pragma unroll
;             for (int ct = 0; ct < 2; ++ct)
; #pragma unroll
;                 for (int e = 0; e < 16; ++e) ya[ct][e] = 0.f;
; #pragma unroll
;             for (int kt = 0; kt < 2; ++kt)
; #pragma unroll
;                 for (int sI = 0; sI < 2; ++sI) { const LAS bf16* ap = imKR + r31 * 72 + 32 * kt + 16 * sI + 4 * hh; const u32x2 lo = *(const LAS u32x2*)ap, hi = *(const LAS u32x2*)(ap + 8);
;                     u32x4 pa; pa.x = lo.x; pa.y = lo.y; pa.z = hi.x; pa.w = hi.y; const bf16x8 af = __builtin_bit_cast(bf16x8, pa);
; #pragma unroll
;                     for (int ct = 0; ct < 2; ++ct) { const f32x16& x = st[kt][ct];
;                         const bf16x8 bfr = pack8s(x[8 * sI], x[8 * sI + 1], x[8 * sI + 2], x[8 * sI + 3], x[8 * sI + 4], x[8 * sI + 5], x[8 * sI + 6], x[8 * sI + 7]);
;                         ya[ct] = __builtin_amdgcn_mfma_f32_32x32x16_bf16(af, bfr, ya[ct], 0, 0, 0); } }
.Lsc1_r1_noload:
	v_mov_b32_e32 v194, s42
	s_ashr_i32 s39, s38, 31
	v_mad_u32_u24 v100, v190, 48, v72
	ds_read_b128 v[64:67], v100 offset:4608
	ds_read_b128 v[68:71], v100
	ds_read_b128 v[80:83], v100 offset:32
	ds_read_b128 v[84:87], v100 offset:4640
	ds_read_b128 v[88:91], v100 offset:4672
	ds_read_b128 v[92:95], v100 offset:4704
	ds_read_b128 v[96:99], v100 offset:64
	ds_read_b128 v[100:103], v100 offset:96
	v_and_b32_e32 v105, 15, v112
	v_cmp_lt_i32_e64 s[2:3], v193, v105
	v_or_b32_e32 v106, 2, v193
	v_cmp_le_i32_e64 s[4:5], v106, v105
	v_cndmask_b32_e64 v107, 0, 1, s[2:3]
	s_waitcnt lgkmcnt(6)
	v_mfma_f32_32x32x16_bf16 v[64:79], v[64:67], v[68:71], 0
	v_cmp_le_i32_e64 s[2:3], v193, v105
	v_mad_u32_u24 v195, v190, s61, v194
	v_add_u32_e32 v104, v195, v104
	s_waitcnt lgkmcnt(0)
	s_waitcnt lgkmcnt(4)
	v_mfma_f32_32x32x16_bf16 v[64:79], v[84:87], v[80:83], v[64:79]
	v_cndmask_b32_e64 v80, 0, 1, s[2:3]
	v_cmp_lt_i32_e64 s[2:3], v106, v105
	v_cndmask_b32_e64 v82, 0, 1, s[4:5]
	s_nop 0
	v_cndmask_b32_e64 v81, 0, 1, s[2:3]
	v_cmp_gt_u32_e64 s[2:3], 16, v190
	s_waitcnt lgkmcnt(1)
	v_mfma_f32_32x32x16_bf16 v[64:79], v[88:91], v[96:99], v[64:79]
	v_cndmask_b32_e64 v81, v82, v81, s[2:3]
	v_or_b32_e32 v82, 4, v193
	v_cndmask_b32_e64 v80, v80, v107, s[2:3]
	v_cmp_lt_i32_e64 s[4:5], v82, v105
	v_and_b32_e32 v80, 1, v80
	v_and_b32_e32 v81, 1, v81
	v_cndmask_b32_e64 v83, 0, 1, s[4:5]
	v_cmp_le_i32_e64 s[4:5], v82, v105
	s_waitcnt lgkmcnt(0)
	v_mfma_f32_32x32x16_bf16 v[64:79], v[92:95], v[100:103], v[64:79]
	v_cmp_eq_u32_e64 s[6:7], 1, v81
	v_cndmask_b32_e64 v82, 0, 1, s[4:5]
	v_cmp_eq_u32_e64 s[4:5], 1, v80
	v_or_b32_e32 v80, 6, v193
	v_cmp_lt_i32_e64 s[10:11], v80, v105
	v_cndmask_b32_e64 v82, v82, v83, s[2:3]
	v_and_b32_e32 v82, 1, v82
	v_cndmask_b32_e64 v81, 0, 1, s[10:11]
	v_cmp_le_i32_e64 s[10:11], v80, v105
	v_cmp_eq_u32_e64 s[8:9], 1, v82
	s_nop 1
	v_cndmask_b32_e64 v64, 0, v64, s[4:5]
	v_cndmask_b32_e64 v80, 0, 1, s[10:11]
	v_cndmask_b32_e64 v80, v80, v81, s[2:3]
	v_and_b32_e32 v80, 1, v80
	v_cmp_eq_u32_e64 s[10:11], 1, v80
	v_cndmask_b32_e64 v65, 0, v65, s[6:7]
	v_cndmask_b32_e64 v66, 0, v66, s[8:9]
	v_cndmask_b32_e64 v67, 0, v67, s[10:11]
	ds_write_b128 v104, v[64:67] offset:4608
	v_or_b32_e32 v65, 3, v193
	v_cmp_lt_i32_e64 s[14:15], v65, v105
	v_cndmask_b32_e64 v64, 0, 1, s[2:3]
	v_or_b32_e32 v64, v193, v64
	v_cndmask_b32_e64 v66, 0, 1, s[14:15]
	v_cmp_le_i32_e64 s[14:15], v65, v105
	v_cmp_gt_i32_e64 s[12:13], v105, v64
	s_nop 0
	v_cndmask_b32_e64 v65, 0, 1, s[14:15]
	v_cndmask_b32_e64 v65, v65, v66, s[2:3]
	v_or_b32_e32 v66, 5, v193
	v_cmp_lt_i32_e64 s[16:17], v66, v105
	v_cndmask_b32_e64 v64, 0, v68, s[12:13]
	v_and_b32_e32 v65, 1, v65
	v_cndmask_b32_e64 v67, 0, 1, s[16:17]
	v_cmp_le_i32_e64 s[16:17], v66, v105
	v_cmp_eq_u32_e64 s[14:15], 1, v65
	s_nop 0
	v_cndmask_b32_e64 v66, 0, 1, s[16:17]
	v_cndmask_b32_e64 v66, v66, v67, s[2:3]
	v_or_b32_e32 v67, 7, v193
	v_cmp_lt_i32_e64 s[18:19], v67, v105
	v_and_b32_e32 v66, 1, v66
	v_cmp_eq_u32_e64 s[16:17], 1, v66
	v_cndmask_b32_e64 v68, 0, 1, s[18:19]
	v_cmp_le_i32_e64 s[18:19], v67, v105
	v_cndmask_b32_e64 v65, 0, v69, s[14:15]
	v_cndmask_b32_e64 v66, 0, v70, s[16:17]
	v_cndmask_b32_e64 v67, 0, 1, s[18:19]
	v_cndmask_b32_e64 v67, v67, v68, s[2:3]
	v_and_b32_e32 v67, 1, v67
	v_cmp_eq_u32_e64 s[2:3], 1, v67
	s_nop 1
	v_cndmask_b32_e64 v67, 0, v71, s[2:3]
	ds_write_b128 v104, v[64:67] offset:4640
	v_cndmask_b32_e64 v64, 0, v72, s[4:5]
	v_cndmask_b32_e64 v65, 0, v73, s[6:7]
	v_cndmask_b32_e64 v66, 0, v74, s[8:9]
	v_cndmask_b32_e64 v67, 0, v75, s[10:11]
	ds_write_b128 v104, v[64:67] offset:4672
	v_cndmask_b32_e64 v64, 0, v76, s[12:13]
	v_cndmask_b32_e64 v65, 0, v77, s[14:15]
	v_cndmask_b32_e64 v66, 0, v78, s[16:17]
	v_cndmask_b32_e64 v67, 0, v79, s[2:3]
	ds_write_b128 v104, v[64:67] offset:4704
	s_waitcnt lgkmcnt(0)
	s_barrier
	v_add_u32_e32 v104, v195, v193
	ds_read2_b64 v[64:67], v104 offset1:2
	v_cvt_pk_bf16_f32 v68, v0, v1
	v_cvt_pk_bf16_f32 v69, v2, v3
	v_cvt_pk_bf16_f32 v70, v4, v5
	v_cvt_pk_bf16_f32 v71, v6, v7
	s_nop 1
	v_mad_u64_u32 v[120:121], s[0:1], v191, 24, v[104:105]
	s_waitcnt lgkmcnt(0)
	v_mfma_f32_32x32x16_bf16 v[80:95], v[64:67], v[68:71], 0
	v_cvt_pk_bf16_f32 v68, v48, v49
	v_cvt_pk_bf16_f32 v69, v50, v51
	v_cvt_pk_bf16_f32 v70, v52, v53
	v_cvt_pk_bf16_f32 v71, v54, v55
	s_nop 1
	ds_read2_b64 v[96:99], v104 offset0:4 offset1:6
	v_cvt_pk_bf16_f32 v100, v8, v9
	v_cvt_pk_bf16_f32 v101, v10, v11
	v_cvt_pk_bf16_f32 v102, v12, v13
	v_cvt_pk_bf16_f32 v103, v14, v15
	s_nop 1
	v_mfma_f32_32x32x16_bf16 v[64:79], v[64:67], v[68:71], 0
	s_waitcnt lgkmcnt(0)
	v_mfma_f32_32x32x16_bf16 v[80:95], v[96:99], v[100:103], v[80:95]
	v_cvt_pk_bf16_f32 v100, v56, v57
	v_cvt_pk_bf16_f32 v101, v58, v59
	v_cvt_pk_bf16_f32 v102, v60, v61
	v_cvt_pk_bf16_f32 v103, v62, v63
	s_nop 1
	s_nop 0
	v_mfma_f32_32x32x16_bf16 v[64:79], v[96:99], v[100:103], v[64:79]
	ds_read2_b64 v[96:99], v104 offset0:8 offset1:10
	v_cvt_pk_bf16_f32 v100, v32, v33
	v_cvt_pk_bf16_f32 v101, v34, v35
	v_cvt_pk_bf16_f32 v102, v36, v37
	v_cvt_pk_bf16_f32 v103, v38, v39
	s_nop 1
	s_waitcnt lgkmcnt(0)
	v_mfma_f32_32x32x16_bf16 v[80:95], v[96:99], v[100:103], v[80:95]
	v_cvt_pk_bf16_f32 v100, v16, v17
	v_cvt_pk_bf16_f32 v101, v18, v19
	v_cvt_pk_bf16_f32 v102, v20, v21
	v_cvt_pk_bf16_f32 v103, v22, v23
	s_nop 1
	s_nop 0
	v_mfma_f32_32x32x16_bf16 v[64:79], v[96:99], v[100:103], v[64:79]
	ds_read2_b64 v[96:99], v104 offset0:12 offset1:14
	v_cvt_pk_bf16_f32 v100, v40, v41
	v_cvt_pk_bf16_f32 v101, v42, v43
	v_cvt_pk_bf16_f32 v102, v44, v45
	v_cvt_pk_bf16_f32 v103, v46, v47
	s_nop 1
	s_waitcnt lgkmcnt(0)
; #define LAS __attribute__((address_space(3)))
; template <int role> __device__ __forceinline__ void ph_scan1m_r(Ctx& C) {
;     ...
;             if (role) { const f32x4 m0 = *(const LAS f32x4*)(MT + r31 * 36 + 16 + 8 * hh), m1 = *(const LAS f32x4*)(MT + r31 * 36 + 20 + 8 * hh); const bf16x8 af = pack8s(m0[0], m0[1], m0[2], m0[3], m1[0], m1[1], m1[2], m1[3]);
; #pragma unroll
;                 for (int ct = 0; ct < 2; ++ct) { vfr[ct] = *(const LAS bf16x8*)(imVT + (32 * ct + r31) * 24 + 8 * hh); ya[ct] = __builtin_amdgcn_mfma_f32_32x32x16_bf16(af, vfr[ct], ya[ct], 0, 0, 0); } }
;             __builtin_amdgcn_sched_barrier(0);
;             f32x2 u2[16];
; #pragma unroll
;             for (int e = 0; e < 4; ++e) {
;                 const auto a0 = __builtin_amdgcn_permlane32_swap(__float_as_uint(ya[0][e]), __float_as_uint(ya[0][e]), false, false), a1 = __builtin_amdgcn_permlane32_swap(__float_as_uint(ya[1][e]), __float_as_uint(ya[1][e]), false, false);
;                 const auto b0 = __builtin_amdgcn_permlane32_swap(__float_as_uint(ya[0][4 + e]), __float_as_uint(ya[0][4 + e]), false, false), b1 = __builtin_amdgcn_permlane32_swap(__float_as_uint(ya[1][4 + e]), __float_as_uint(ya[1][4 + e]), false, false);
;                 u2[e] = (f32x2){__uint_as_float(a0[0]), __uint_as_float(a1[0])}; u2[4 + e] = (f32x2){__uint_as_float(a0[1]), __uint_as_float(a1[1])};
;                 u2[8 + e] = (f32x2){__uint_as_float(b0[0]), __uint_as_float(b1[0])}; u2[12 + e] = (f32x2){__uint_as_float(b0[1]), __uint_as_float(b1[1])}; }
; #pragma unroll
;             for (int t = 1; t < 16; ++t) { f32x2 a = u2[t]; float clast = 0.f;
; #pragma unroll
;                 for (int q = 0; q < 4; ++q) { const int smin = q < 2 ? 8 * q : 8 * (q - 2) + 1;
;                     if (smin < t) { const f32x4 cf = *(const LAS f32x4*)(MT + t * 36 + 4 * q);
; #pragma unroll
;                         for (int e = 0; e < 4; ++e) { const int sl = 4 * q + e, st_ = sl < 8 ? 2 * sl : 2 * (sl - 8) + 1; if (st_ == t - 1) clast = cf[e]; else if (st_ < t) a += u2[st_] * cf[e]; } } }
;                 a += u2[t - 1] * clast;
;                 u2[t] = a; }
	v_mfma_f32_32x32x16_bf16 v[80:95], v[96:99], v[100:103], v[80:95]
	v_cvt_pk_bf16_f32 v100, v24, v25
	v_cvt_pk_bf16_f32 v101, v26, v27
	v_cvt_pk_bf16_f32 v102, v28, v29
	v_cvt_pk_bf16_f32 v103, v30, v31
	s_nop 1
	ds_read_b128 v[104:107], v120 offset:4672
	ds_read_b128 v[108:111], v120 offset:4688
	s_waitcnt lgkmcnt(0)
	v_cvt_pk_bf16_f32 v122, v104, v105
	v_cvt_pk_bf16_f32 v123, v106, v107
	v_cvt_pk_bf16_f32 v124, v108, v109
	v_cvt_pk_bf16_f32 v125, v110, v111
	s_nop 1
	v_mfma_f32_32x32x16_bf16 v[64:79], v[96:99], v[100:103], v[64:79]
	v_mad_u32_u24 v96, v190, 48, v192
	ds_read_b128 v[100:103], v96 offset:14592
	ds_read_b128 v[96:99], v96 offset:16128
	s_waitcnt lgkmcnt(1)
	v_mfma_f32_32x32x16_bf16 v[80:95], v[122:125], v[100:103], v[80:95]
	s_waitcnt lgkmcnt(0)
	v_mfma_f32_32x32x16_bf16 v[64:79], v[122:125], v[96:99], v[64:79]
	v_add_u32_e32 v121, 0x1000, v194
	ds_read2_b32 v[126:127], v121 offset0:164 offset1:200
	s_nop 7
	v_mov_b32_e32 v104, v80
	v_mov_b32_e32 v138, v80
	v_mov_b32_e32 v105, v64
	v_mov_b32_e32 v139, v64
	v_mov_b32_e32 v106, v81
	v_mov_b32_e32 v196, v81
	v_mov_b32_e32 v107, v65
	v_mov_b32_e32 v197, v65
	v_permlane32_swap_b32_e32 v104, v138
	v_permlane32_swap_b32_e32 v105, v139
	v_permlane32_swap_b32_e32 v106, v196
	v_permlane32_swap_b32_e32 v107, v197
	v_mov_b32_e32 v122, v82
	v_mov_b32_e32 v200, v82
	v_mov_b32_e32 v123, v66
	v_mov_b32_e32 v201, v66
	v_permlane32_swap_b32_e32 v122, v200
	s_nop 0
	v_permlane32_swap_b32_e32 v123, v201
	s_waitcnt lgkmcnt(0)
	v_pk_fma_f32 v[106:107], v[126:127], v[104:105], v[106:107] op_sel_hi:[0,1,1]
	v_mov_b32_e32 v126, v127
	v_pk_fma_f32 v[122:123], v[126:127], v[104:105], v[122:123] op_sel_hi:[0,1,1]
	ds_read_b32 v198, v194 offset:4928
	ds_read_b64 v[204:205], v194 offset:5040
	ds_read_b32 v206, v194 offset:5072
	ds_read2_b64 v[126:129], v121 offset0:136 offset1:140
	ds_read_b96 v[130:132], v194 offset:5328
	v_mov_b32_e32 v124, v83
	v_mov_b32_e32 v202, v83
	v_mov_b32_e32 v125, v67
	v_mov_b32_e32 v203, v67
	v_permlane32_swap_b32_e32 v124, v202
	s_nop 0
	v_permlane32_swap_b32_e32 v125, v203
	s_waitcnt lgkmcnt(4)
	v_pk_fma_f32 v[122:123], v[106:107], v[198:199], v[122:123] op_sel_hi:[1,0,1]
	s_waitcnt lgkmcnt(3)
	v_pk_fma_f32 v[124:125], v[204:205], v[104:105], v[124:125] op_sel_hi:[0,1,1]
	s_waitcnt lgkmcnt(1)
	v_pk_fma_f32 v[138:139], v[126:127], v[104:105], v[138:139] op_sel_hi:[0,1,1]
	v_pk_fma_f32 v[124:125], v[106:107], v[206:207], v[124:125] op_sel_hi:[1,0,1]
	v_pk_fma_f32 v[126:127], v[122:123], v[126:127], v[138:139] op_sel:[0,1,0]
	ds_read_b64 v[138:139], v194 offset:5360
	v_pk_fma_f32 v[124:125], v[204:205], v[122:123], v[124:125] op_sel:[1,0,0]
	v_pk_fma_f32 v[126:127], v[106:107], v[128:129], v[126:127] op_sel_hi:[1,0,1]
	ds_read_b96 v[204:206], v194 offset:5648
	v_pk_fma_f32 v[126:127], v[128:129], v[124:125], v[126:127] op_sel:[1,0,0]
	s_waitcnt lgkmcnt(2)
	v_pk_fma_f32 v[128:129], v[130:131], v[104:105], v[196:197] op_sel_hi:[0,1,1]
	ds_read_b96 v[196:198], v194 offset:5472
	v_pk_fma_f32 v[128:129], v[122:123], v[130:131], v[128:129] op_sel:[0,1,0]
	v_mov_b32_e32 v130, v132
	s_waitcnt lgkmcnt(2)
	v_pk_fma_f32 v[128:129], v[106:107], v[138:139], v[128:129] op_sel_hi:[1,0,1]
	v_mov_b32_e32 v208, v84
	v_pk_fma_f32 v[128:129], v[124:125], v[138:139], v[128:129] op_sel:[0,1,0]
	s_waitcnt lgkmcnt(0)
	v_pk_fma_f32 v[138:139], v[196:197], v[104:105], v[200:201] op_sel_hi:[0,1,1]
	v_pk_fma_f32 v[128:129], v[130:131], v[126:127], v[128:129] op_sel_hi:[0,1,1]
	ds_read_b96 v[130:132], v194 offset:5504
	v_pk_fma_f32 v[138:139], v[122:123], v[196:197], v[138:139] op_sel:[0,1,0]
	v_mov_b32_e32 v196, v198
	v_pk_fma_f32 v[138:139], v[196:197], v[126:127], v[138:139] op_sel_hi:[0,1,1]
	ds_read_b128 v[196:199], v194 offset:5616
	s_waitcnt lgkmcnt(1)
	v_pk_fma_f32 v[138:139], v[106:107], v[130:131], v[138:139] op_sel_hi:[1,0,1]
	v_mov_b32_e32 v136, v84
	v_pk_fma_f32 v[130:131], v[124:125], v[130:131], v[138:139] op_sel:[0,1,0]
	v_mov_b32_e32 v209, v68
	v_pk_fma_f32 v[130:131], v[132:133], v[128:129], v[130:131] op_sel_hi:[0,1,1]
	s_waitcnt lgkmcnt(0)
	v_pk_fma_f32 v[132:133], v[196:197], v[104:105], v[202:203] op_sel_hi:[0,1,1]
	v_pk_fma_f32 v[132:133], v[122:123], v[196:197], v[132:133] op_sel:[0,1,0]
	ds_read_b128 v[200:203], v194 offset:5760
	v_pk_fma_f32 v[132:133], v[126:127], v[198:199], v[132:133] op_sel_hi:[1,0,1]
	v_mov_b32_e32 v137, v68
	v_pk_fma_f32 v[132:133], v[106:107], v[204:205], v[132:133] op_sel_hi:[1,0,1]
	v_mov_b32_e32 v138, v206
	v_pk_fma_f32 v[132:133], v[124:125], v[204:205], v[132:133] op_sel:[0,1,0]
	v_permlane32_swap_b32_e32 v208, v136
	v_permlane32_swap_b32_e32 v209, v137
	v_pk_fma_f32 v[132:133], v[138:139], v[128:129], v[132:133] op_sel_hi:[0,1,1]
	v_mov_b32_e32 v138, v199
	v_pk_fma_f32 v[132:133], v[138:139], v[130:131], v[132:133] op_sel_hi:[0,1,1]
	s_waitcnt lgkmcnt(0)
	v_pk_fma_f32 v[138:139], v[200:201], v[104:105], v[208:209] op_sel_hi:[0,1,1]
	ds_read_b128 v[196:199], v194 offset:5792
	v_pk_fma_f32 v[138:139], v[122:123], v[200:201], v[138:139] op_sel:[0,1,0]
	v_mov_b32_e32 v200, v203
	v_pk_fma_f32 v[138:139], v[126:127], v[202:203], v[138:139] op_sel_hi:[1,0,1]
	v_mov_b32_e32 v210, v85
	v_pk_fma_f32 v[138:139], v[200:201], v[130:131], v[138:139] op_sel_hi:[0,1,1]
	ds_read_b128 v[200:203], v194 offset:5904
	s_waitcnt lgkmcnt(1)
	v_pk_fma_f32 v[138:139], v[106:107], v[196:197], v[138:139] op_sel_hi:[1,0,1]
	v_mov_b32_e32 v134, v85
	v_mov_b32_e32 v211, v69
	v_mov_b32_e32 v135, v69
	v_pk_fma_f32 v[138:139], v[124:125], v[196:197], v[138:139] op_sel:[0,1,0]
	v_permlane32_swap_b32_e32 v210, v134
	v_permlane32_swap_b32_e32 v211, v135
	v_pk_fma_f32 v[138:139], v[128:129], v[198:199], v[138:139] op_sel_hi:[1,0,1]
	v_mov_b32_e32 v196, v199
	v_pk_fma_f32 v[138:139], v[196:197], v[132:133], v[138:139] op_sel_hi:[0,1,1]
	s_waitcnt lgkmcnt(0)
; #define LAS __attribute__((address_space(3)))
; template <int role> __device__ __forceinline__ void ph_scan1m_r(Ctx& C) {
;     ...
;             for (int t = 1; t < 16; ++t) { f32x2 a = u2[t]; float clast = 0.f;
; #pragma unroll
;                 for (int q = 0; q < 4; ++q) { const int smin = q < 2 ? 8 * q : 8 * (q - 2) + 1;
;                     if (smin < t) { const f32x4 cf = *(const LAS f32x4*)(MT + t * 36 + 4 * q);
; #pragma unroll
;                         for (int e = 0; e < 4; ++e) { const int sl = 4 * q + e, st_ = sl < 8 ? 2 * sl : 2 * (sl - 8) + 1; if (st_ == t - 1) clast = cf[e]; else if (st_ < t) a += u2[st_] * cf[e]; } } }
;                 a += u2[t - 1] * clast;
;                 u2[t] = a; }
	v_pk_fma_f32 v[196:197], v[200:201], v[104:105], v[210:211] op_sel_hi:[0,1,1]
	v_pk_fma_f32 v[196:197], v[122:123], v[200:201], v[196:197] op_sel:[0,1,0]
	v_add_u32_e32 v121, 0x1400, v194
	v_pk_fma_f32 v[200:201], v[126:127], v[202:203], v[196:197] op_sel_hi:[1,0,1]
	ds_read_b128 v[196:199], v194 offset:5936
	v_mov_b32_e32 v202, v203
	v_pk_fma_f32 v[204:205], v[202:203], v[130:131], v[200:201] op_sel_hi:[0,1,1]
	ds_read2_b32 v[206:207], v121 offset0:200 offset1:236
	ds_read_b128 v[200:203], v194 offset:6048
	v_mov_b32_e32 v212, v86
	s_waitcnt lgkmcnt(2)
	v_pk_fma_f32 v[204:205], v[106:107], v[196:197], v[204:205] op_sel_hi:[1,0,1]
	v_mov_b32_e32 v110, v86
	v_pk_fma_f32 v[196:197], v[124:125], v[196:197], v[204:205] op_sel:[0,1,0]
	v_mov_b32_e32 v213, v70
	v_mov_b32_e32 v111, v70
	v_pk_fma_f32 v[196:197], v[128:129], v[198:199], v[196:197] op_sel_hi:[1,0,1]
	v_mov_b32_e32 v198, v199
	v_permlane32_swap_b32_e32 v212, v110
	v_permlane32_swap_b32_e32 v213, v111
	v_pk_fma_f32 v[196:197], v[198:199], v[132:133], v[196:197] op_sel_hi:[0,1,1]
	s_waitcnt lgkmcnt(1)
	v_pk_fma_f32 v[208:209], v[206:207], v[138:139], v[196:197] op_sel_hi:[0,1,1]
	s_waitcnt lgkmcnt(0)
	v_pk_fma_f32 v[196:197], v[200:201], v[104:105], v[212:213] op_sel_hi:[0,1,1]
	v_pk_fma_f32 v[196:197], v[122:123], v[200:201], v[196:197] op_sel:[0,1,0]
	ds_read_b32 v204, v194 offset:6096
	v_pk_fma_f32 v[200:201], v[126:127], v[202:203], v[196:197] op_sel_hi:[1,0,1]
	ds_read_b128 v[196:199], v194 offset:6080
	v_mov_b32_e32 v202, v203
	v_pk_fma_f32 v[200:201], v[130:131], v[202:203], v[200:201] op_sel_hi:[1,0,1]
	v_mov_b32_e32 v202, v207
	v_pk_fma_f32 v[200:201], v[202:203], v[138:139], v[200:201] op_sel_hi:[0,1,1]
	s_waitcnt lgkmcnt(0)
	v_pk_fma_f32 v[200:201], v[106:107], v[196:197], v[200:201] op_sel_hi:[1,0,1]
	v_mov_b32_e32 v214, v87
	v_pk_fma_f32 v[196:197], v[124:125], v[196:197], v[200:201] op_sel:[0,1,0]
	ds_read_b128 v[200:203], v194 offset:6192
	v_mov_b32_e32 v108, v87
	v_mov_b32_e32 v215, v71
	v_mov_b32_e32 v109, v71
	v_pk_fma_f32 v[196:197], v[128:129], v[198:199], v[196:197] op_sel_hi:[1,0,1]
	v_mov_b32_e32 v198, v199
	v_permlane32_swap_b32_e32 v214, v108
	v_permlane32_swap_b32_e32 v215, v109
	v_pk_fma_f32 v[196:197], v[132:133], v[198:199], v[196:197] op_sel_hi:[1,0,1]
	v_add_u32_e32 v121, 0x1800, v194
	v_pk_fma_f32 v[210:211], v[204:205], v[208:209], v[196:197] op_sel_hi:[0,1,1]
	ds_read_b64 v[204:205], v194 offset:6208
	s_waitcnt lgkmcnt(1)
	v_pk_fma_f32 v[196:197], v[200:201], v[104:105], v[214:215] op_sel_hi:[0,1,1]
	v_pk_fma_f32 v[196:197], v[122:123], v[200:201], v[196:197] op_sel:[0,1,0]
	s_nop 0
	v_pk_fma_f32 v[200:201], v[126:127], v[202:203], v[196:197] op_sel_hi:[1,0,1]
	ds_read_b128 v[196:199], v194 offset:6224
	v_mov_b32_e32 v202, v203
	v_pk_fma_f32 v[200:201], v[130:131], v[202:203], v[200:201] op_sel_hi:[1,0,1]
	ds_read_b32 v202, v194 offset:6240
	s_waitcnt lgkmcnt(2)
	v_pk_fma_f32 v[200:201], v[138:139], v[204:205], v[200:201] op_sel_hi:[1,0,1]
	s_waitcnt lgkmcnt(1)
	v_mov_b32_e32 v206, v199
	v_pk_fma_f32 v[200:201], v[106:107], v[196:197], v[200:201] op_sel_hi:[1,0,1]
	s_nop 0
	v_pk_fma_f32 v[196:197], v[124:125], v[196:197], v[200:201] op_sel:[0,1,0]
	s_nop 0
	v_pk_fma_f32 v[200:201], v[128:129], v[198:199], v[196:197] op_sel_hi:[1,0,1]
	ds_read_b128 v[196:199], v194 offset:6336
	v_pk_fma_f32 v[200:201], v[132:133], v[206:207], v[200:201] op_sel_hi:[1,0,1]
	s_waitcnt lgkmcnt(1)
	v_pk_fma_f32 v[200:201], v[202:203], v[208:209], v[200:201] op_sel_hi:[0,1,1]
	v_pk_fma_f32 v[212:213], v[204:205], v[210:211], v[200:201] op_sel:[1,0,0]
	ds_read2_b64 v[204:207], v121 offset0:26 offset1:30
	ds_read_b128 v[200:203], v194 offset:6368
	s_waitcnt lgkmcnt(2)
	v_pk_fma_f32 v[136:137], v[196:197], v[104:105], v[136:137] op_sel_hi:[0,1,1]
	v_pk_fma_f32 v[136:137], v[122:123], v[196:197], v[136:137] op_sel:[0,1,0]
	v_mov_b32_e32 v196, v199
	v_pk_fma_f32 v[136:137], v[126:127], v[198:199], v[136:137] op_sel_hi:[1,0,1]
	v_cndmask_b32_e32 v121, v128, v126, vcc
	v_pk_fma_f32 v[136:137], v[130:131], v[196:197], v[136:137] op_sel_hi:[1,0,1]
	ds_read_b128 v[196:199], v194 offset:6480
	s_waitcnt lgkmcnt(2)
	v_pk_fma_f32 v[136:137], v[138:139], v[204:205], v[136:137] op_sel_hi:[1,0,1]
	s_nop 0
	v_pk_fma_f32 v[136:137], v[204:205], v[210:211], v[136:137] op_sel:[1,0,0]
	s_waitcnt lgkmcnt(1)
	v_pk_fma_f32 v[136:137], v[106:107], v[200:201], v[136:137] op_sel_hi:[1,0,1]
	s_nop 0
	v_pk_fma_f32 v[136:137], v[124:125], v[200:201], v[136:137] op_sel:[0,1,0]
	v_mov_b32_e32 v200, v203
	v_pk_fma_f32 v[136:137], v[128:129], v[202:203], v[136:137] op_sel_hi:[1,0,1]
	s_nop 0
	v_pk_fma_f32 v[136:137], v[132:133], v[200:201], v[136:137] op_sel_hi:[1,0,1]
	ds_read_b96 v[200:202], v194 offset:6496
	s_waitcnt lgkmcnt(1)
	v_pk_fma_f32 v[134:135], v[196:197], v[104:105], v[134:135] op_sel_hi:[0,1,1]
	v_pk_fma_f32 v[136:137], v[208:209], v[206:207], v[136:137] op_sel_hi:[1,0,1]
	v_pk_fma_f32 v[134:135], v[122:123], v[196:197], v[134:135] op_sel:[0,1,0]
	v_pk_fma_f32 v[204:205], v[206:207], v[212:213], v[136:137] op_sel:[1,0,0]
	v_pk_fma_f32 v[196:197], v[126:127], v[198:199], v[134:135] op_sel_hi:[1,0,1]
	ds_read_b128 v[134:137], v194 offset:6512
	v_mov_b32_e32 v198, v199
	v_pk_fma_f32 v[196:197], v[130:131], v[198:199], v[196:197] op_sel_hi:[1,0,1]
	ds_read_b64 v[198:199], v194 offset:6528
	s_waitcnt lgkmcnt(2)
	v_pk_fma_f32 v[196:197], v[138:139], v[200:201], v[196:197] op_sel_hi:[1,0,1]
	s_nop 0
	v_pk_fma_f32 v[196:197], v[210:211], v[200:201], v[196:197] op_sel:[0,1,0]
	s_waitcnt lgkmcnt(1)
; #define LAS __attribute__((address_space(3)))
; __device__ __forceinline__ unsigned cvt_pk_bf16(float lo, float hi) { unsigned r; asm volatile("v_cvt_pk_bf16_f32 %0, %1, %2" : "=v"(r) : "v"(lo), "v"(hi)); return r; }
; template <int role> __device__ __forceinline__ void ph_scan1m_r(Ctx& C) {
;     ...
;                 u2[t] = a; }
;             bf16x8 ufr[2];
;             ufr[0] = pack8s(hh ? u2[1].x : u2[0].x, hh ? u2[3].x : u2[2].x, hh ? u2[5].x : u2[4].x, hh ? u2[7].x : u2[6].x, hh ? u2[9].x : u2[8].x, hh ? u2[11].x : u2[10].x, hh ? u2[13].x : u2[12].x, hh ? u2[15].x : u2[14].x);
;             ufr[1] = pack8s(hh ? u2[1].y : u2[0].y, hh ? u2[3].y : u2[2].y, hh ? u2[5].y : u2[4].y, hh ? u2[7].y : u2[6].y, hh ? u2[9].y : u2[8].y, hh ? u2[11].y : u2[10].y, hh ? u2[13].y : u2[12].y, hh ? u2[15].y : u2[14].y);
;             __builtin_amdgcn_sched_barrier(0);
;             { const f32x4 m0 = *(const LAS f32x4*)(MT + r31 * 36 + 8 * hh), m1 = *(const LAS f32x4*)(MT + r31 * 36 + 4 + 8 * hh); const bf16x8 af = pack8s(m0[0], m0[1], m0[2], m0[3], m1[0], m1[1], m1[2], m1[3]);
; #pragma unroll
;               for (int ct = 0; ct < 2; ++ct) ya[ct] = __builtin_amdgcn_mfma_f32_32x32x16_bf16(af, ufr[ct], ya[ct], 0, 0, 0); }
;             { LAS bf16* ys = (LAS bf16*)MT;
; #pragma unroll
;               for (int ct = 0; ct < 2; ++ct)
; #pragma unroll
;                   for (int e = 0; e < 8; e += 2) { const unsigned pw = pg8::cvt_pk_bf16(ya[ct][8 + e], ya[ct][9 + e]); const int t = (e & 3) + 4 * hh + 8 * (e >> 2); LAS bf16* d = ys + t * 72 + 32 * ct + r31; d[0] = (bf16)pw; d[72] = (bf16)(pw >> 16); }
;               asm volatile("s_waitcnt lgkmcnt(0)" ::: "memory");
; #pragma unroll
;               for (int i = 0; i < 2; ++i) { const int t = (lane >> 3) + 8 * i; const u32x4 w = *(const LAS u32x4*)(ys + t * 72 + 8 * (lane & 7)); *(u32x4*)(g_out + zoff + rowu + (long)t * dix + 8 * (lane & 7)) = w; }
;               asm volatile("s_waitcnt lgkmcnt(0)" ::: "memory"); }
	v_pk_fma_f32 v[196:197], v[106:107], v[134:135], v[196:197] op_sel_hi:[1,0,1]
	s_nop 0
	v_pk_fma_f32 v[134:135], v[124:125], v[134:135], v[196:197] op_sel:[0,1,0]
	s_nop 0
	v_pk_fma_f32 v[134:135], v[128:129], v[136:137], v[134:135] op_sel_hi:[1,0,1]
	v_mov_b32_e32 v136, v137
	v_pk_fma_f32 v[134:135], v[132:133], v[136:137], v[134:135] op_sel_hi:[1,0,1]
	s_waitcnt lgkmcnt(0)
	v_pk_fma_f32 v[196:197], v[208:209], v[198:199], v[134:135] op_sel_hi:[1,0,1]
	ds_read_b128 v[134:137], v194 offset:6624
	v_pk_fma_f32 v[196:197], v[198:199], v[212:213], v[196:197] op_sel:[1,0,0]
	v_mov_b32_e32 v198, v202
	v_pk_fma_f32 v[200:201], v[198:199], v[204:205], v[196:197] op_sel_hi:[0,1,1]
	ds_read_b96 v[196:198], v194 offset:6640
	s_waitcnt lgkmcnt(1)
	v_pk_fma_f32 v[110:111], v[134:135], v[104:105], v[110:111] op_sel_hi:[0,1,1]
	v_pk_fma_f32 v[110:111], v[122:123], v[134:135], v[110:111] op_sel:[0,1,0]
	v_mov_b32_e32 v134, v137
	v_pk_fma_f32 v[110:111], v[126:127], v[136:137], v[110:111] op_sel_hi:[1,0,1]
	s_nop 0
	v_pk_fma_f32 v[110:111], v[130:131], v[134:135], v[110:111] op_sel_hi:[1,0,1]
	ds_read_b128 v[134:137], v194 offset:6656
	s_waitcnt lgkmcnt(1)
	v_pk_fma_f32 v[110:111], v[138:139], v[196:197], v[110:111] op_sel_hi:[1,0,1]
	s_nop 0
	v_pk_fma_f32 v[110:111], v[210:211], v[196:197], v[110:111] op_sel:[0,1,0]
	v_mov_b32_e32 v196, v198
	v_pk_fma_f32 v[110:111], v[196:197], v[204:205], v[110:111] op_sel_hi:[0,1,1]
	ds_read_b96 v[196:198], v194 offset:6672
	s_waitcnt lgkmcnt(1)
	v_pk_fma_f32 v[110:111], v[106:107], v[134:135], v[110:111] op_sel_hi:[1,0,1]
	s_nop 0
	v_pk_fma_f32 v[110:111], v[124:125], v[134:135], v[110:111] op_sel:[0,1,0]
	v_mov_b32_e32 v134, v137
	v_pk_fma_f32 v[110:111], v[128:129], v[136:137], v[110:111] op_sel_hi:[1,0,1]
	s_nop 0
	v_pk_fma_f32 v[110:111], v[132:133], v[134:135], v[110:111] op_sel_hi:[1,0,1]
	ds_read_b128 v[134:137], v194 offset:6768
	s_waitcnt lgkmcnt(1)
	v_pk_fma_f32 v[110:111], v[208:209], v[196:197], v[110:111] op_sel_hi:[1,0,1]
	s_nop 0
	v_pk_fma_f32 v[110:111], v[212:213], v[196:197], v[110:111] op_sel:[0,1,0]
	v_mov_b32_e32 v196, v198
	v_pk_fma_f32 v[202:203], v[196:197], v[200:201], v[110:111] op_sel_hi:[0,1,1]
	ds_read_b128 v[196:199], v194 offset:6784
	s_waitcnt lgkmcnt(1)
	v_pk_fma_f32 v[108:109], v[134:135], v[104:105], v[108:109] op_sel_hi:[0,1,1]
	v_pk_fma_f32 v[108:109], v[122:123], v[134:135], v[108:109] op_sel:[0,1,0]
	v_mov_b32_e32 v110, v137
	v_pk_fma_f32 v[108:109], v[126:127], v[136:137], v[108:109] op_sel_hi:[1,0,1]
	v_cndmask_b32_e32 v104, v106, v104, vcc
	v_pk_fma_f32 v[134:135], v[130:131], v[110:111], v[108:109] op_sel_hi:[1,0,1]
	ds_read_b128 v[108:111], v194 offset:6800
	s_waitcnt lgkmcnt(1)
	v_pk_fma_f32 v[134:135], v[138:139], v[196:197], v[134:135] op_sel_hi:[1,0,1]
	v_cndmask_b32_e32 v126, v212, v210, vcc
	v_pk_fma_f32 v[134:135], v[210:211], v[196:197], v[134:135] op_sel:[0,1,0]
	s_nop 0
	v_pk_fma_f32 v[196:197], v[198:199], v[204:205], v[134:135] op_sel_hi:[0,1,1]
	ds_read_b96 v[134:136], v194 offset:6816
	s_waitcnt lgkmcnt(1)
	v_pk_fma_f32 v[196:197], v[106:107], v[108:109], v[196:197] op_sel_hi:[1,0,1]
	v_cndmask_b32_e32 v106, v124, v122, vcc
	v_pk_fma_f32 v[108:109], v[124:125], v[108:109], v[196:197] op_sel:[0,1,0]
	v_cndmask_b32_e32 v122, v132, v130, vcc
	v_pk_fma_f32 v[108:109], v[128:129], v[110:111], v[108:109] op_sel_hi:[1,0,1]
	v_mov_b32_e32 v110, v111
	v_pk_fma_f32 v[108:109], v[132:133], v[110:111], v[108:109] op_sel_hi:[1,0,1]
	s_waitcnt lgkmcnt(0)
	v_mov_b32_e32 v110, v136
	v_pk_fma_f32 v[108:109], v[208:209], v[134:135], v[108:109] op_sel_hi:[1,0,1]
	v_cndmask_b32_e32 v124, v208, v138, vcc
	v_pk_fma_f32 v[108:109], v[212:213], v[134:135], v[108:109] op_sel:[0,1,0]
	v_cndmask_b32_e32 v128, v200, v204, vcc
	v_pk_fma_f32 v[108:109], v[110:111], v[200:201], v[108:109] op_sel_hi:[0,1,1]
	v_mov_b32_e32 v110, v199
	v_pk_fma_f32 v[134:135], v[110:111], v[202:203], v[108:109] op_sel_hi:[0,1,1]
	v_cndmask_b32_e32 v130, v134, v202, vcc
	v_cvt_pk_bf16_f32 v108, v104, v106
	v_cvt_pk_bf16_f32 v109, v121, v122
	v_cvt_pk_bf16_f32 v110, v124, v126
	v_cvt_pk_bf16_f32 v111, v128, v130
	s_nop 1
	v_cndmask_b32_e32 v121, v107, v105, vcc
	v_cndmask_b32_e32 v122, v125, v123, vcc
	v_cndmask_b32_e32 v123, v129, v127, vcc
	v_cndmask_b32_e32 v124, v133, v131, vcc
	v_cndmask_b32_e32 v125, v209, v139, vcc
	v_cndmask_b32_e32 v126, v213, v211, vcc
	v_cndmask_b32_e32 v127, v201, v205, vcc
	v_cndmask_b32_e32 v128, v135, v203, vcc
	v_cvt_pk_bf16_f32 v104, v121, v122
	v_cvt_pk_bf16_f32 v105, v123, v124
	v_cvt_pk_bf16_f32 v106, v125, v126
	v_cvt_pk_bf16_f32 v107, v127, v128
	s_nop 1
	ds_read_b128 v[122:125], v120 offset:4608
	ds_read_b128 v[126:129], v120 offset:4624
	s_lshl_b64 s[0:1], s[38:39], 11
	s_add_u32 s0, s73, s0
	s_addc_u32 s1, s74, s1
	s_waitcnt lgkmcnt(0)
	s_barrier
	v_cvt_pk_bf16_f32 v130, v122, v123
	v_cvt_pk_bf16_f32 v131, v124, v125
	v_cvt_pk_bf16_f32 v132, v126, v127
	v_cvt_pk_bf16_f32 v133, v128, v129
	s_nop 1
	s_nop 0
	v_mfma_f32_32x32x16_bf16 v[80:95], v[130:133], v[108:111], v[80:95]
	v_mfma_f32_32x32x16_bf16 v[64:79], v[130:133], v[104:107], v[64:79]
	s_nop 10
	v_mul_i32_i24_e32 v80, 0xffffff72, v190
	v_mul_lo_u32 v81, v191, s68
	v_add3_u32 v80, v195, v80, v81
	v_cvt_pk_bf16_f32 v81, v88, v89
	ds_write_b16 v80, v81 offset:4608
	ds_write_b16_d16_hi v80, v81 offset:4752
	v_cvt_pk_bf16_f32 v64, v90, v91
	ds_write_b16 v80, v64 offset:4896
	ds_write_b16_d16_hi v80, v64 offset:5040
	v_cvt_pk_bf16_f32 v64, v92, v93
	ds_write_b16 v80, v64 offset:5760
	ds_write_b16_d16_hi v80, v64 offset:5904
	v_cvt_pk_bf16_f32 v64, v94, v95
	ds_write_b16 v80, v64 offset:6048
	ds_write_b16_d16_hi v80, v64 offset:6192
	v_cvt_pk_bf16_f32 v64, v72, v73
	ds_write_b16 v80, v64 offset:4672
	ds_write_b16_d16_hi v80, v64 offset:4816
	v_cvt_pk_bf16_f32 v64, v74, v75
	ds_write_b16 v80, v64 offset:4960
	ds_write_b16_d16_hi v80, v64 offset:5104
	v_cvt_pk_bf16_f32 v64, v76, v77
	ds_write_b16 v80, v64 offset:5824
	ds_write_b16_d16_hi v80, v64 offset:5968
	v_cvt_pk_bf16_f32 v64, v78, v79
	ds_write_b16 v80, v64 offset:6112
	ds_write_b16_d16_hi v80, v64 offset:6256
	v_ashrrev_i32_e32 v76, 3, v112
	v_lshlrev_b32_e32 v64, 4, v112
	v_and_b32_e32 v112, 0x70, v64
	v_mul_lo_u32 v64, v76, s61
	s_waitcnt lgkmcnt(0)
	v_add3_u32 v70, s42, v112, v64
	ds_read_b128 v[64:67], v70 offset:4608
	v_ashrrev_i32_e32 v68, 31, v76
	v_lshl_add_u64 v[72:73], s[0:1], 0, v[112:113]
	v_mul_lo_u32 v71, s34, v68
	v_mul_lo_u32 v74, s35, v76
	v_mad_u64_u32 v[68:69], s[0:1], s34, v76, 0
	v_add3_u32 v69, v69, v71, v74
	v_lshl_add_u64 v[74:75], v[68:69], 1, v[72:73]
	ds_read_b128 v[68:71], v70 offset:5760
	s_waitcnt lgkmcnt(1)
	global_store_dwordx4 v[74:75], v[64:67], off
	s_nop 1
	v_add_u32_e32 v64, 8, v76
	v_ashrrev_i32_e32 v65, 31, v64
	v_mul_lo_u32 v66, s34, v65
	v_mul_lo_u32 v67, s35, v64
	v_mad_u64_u32 v[64:65], s[0:1], s34, v64, 0
	v_add3_u32 v65, v65, v66, v67
	v_lshl_add_u64 v[64:65], v[64:65], 1, v[72:73]
	s_waitcnt lgkmcnt(0)
	global_store_dwordx4 v[64:65], v[68:71], off
	s_waitcnt lgkmcnt(0)
	s_branch .LBB0_708

; template <int role> __device__ __forceinline__ void ph_scan1m_r(Ctx& C) {
;     ...
;             asm volatile("s_waitcnt lgkmcnt(0)" ::: "memory");
;             __builtin_amdgcn_sched_barrier(0);
;             { f32x16 m;
; #pragma unroll
;               for (int e = 0; e < 16; ++e) m[e] = 0.f;
; #pragma unroll
;               for (int ks = 0; ks < 4; ++ks) { const bf16x8 af = *(const LAS bf16x8*)(imBK + r31 * 72 + 16 * ks + 8 * hh), bfr = *(const LAS bf16x8*)(imKR + r31 * 72 + 16 * ks + 8 * hh); m = __builtin_amdgcn_mfma_f32_32x32x16_bf16(af, bfr, m, 0, 0, 0); }
;               asm volatile("s_waitcnt lgkmcnt(0)" ::: "memory");
;               const int tq = r31 & 15; const bool ycol = r31 >= 16;
; #pragma unroll
;               for (int g = 0; g < 4; ++g) { f32x4 o;
; #pragma unroll
;                   for (int e = 0; e < 4; ++e) { const int sq = 2 * (4 * hh + e) + (g & 1); const bool ok = ycol ? (sq <= tq) : (sq < tq); o[e] = ok ? m[4 * g + e] : 0.f; }
;                   *(LAS f32x4*)(MT + r31 * 36 + 8 * g + 4 * hh) = o; } }
;             asm volatile("s_waitcnt lgkmcnt(0)" ::: "memory");
;             __builtin_amdgcn_sched_barrier(0);
;             f32x16 ya[2];
; #pragma unroll
;             for (int ct = 0; ct < 2; ++ct)
; #pragma unroll
;                 for (int e = 0; e < 16; ++e) ya[ct][e] = 0.f;
; #pragma unroll
;             for (int kt = 0; kt < 2; ++kt)
; #pragma unroll
;                 for (int sI = 0; sI < 2; ++sI) { const LAS bf16* ap = imKR + r31 * 72 + 32 * kt + 16 * sI + 4 * hh; const u32x2 lo = *(const LAS u32x2*)ap, hi = *(const LAS u32x2*)(ap + 8);
;     ...
;             for (int kt = 0; kt < 2; ++kt) { f32x4 gs[4];
; #pragma unroll
;                 for (int g = 0; g < 4; ++g) gs[g] = *(const LAS f32x4*)(gT + 32 * kt + 8 * g + 4 * hh);
;                 const bf16x8 au = *(const LAS bf16x8*)(imBGT + (32 * kt + r31) * 40 + 8 * hh); bf16x8 av; if (role) av = *(const LAS bf16x8*)(imBGT + (32 * kt + r31) * 40 + 16 + 8 * hh);
; #pragma unroll
;                 for (int ct = 0; ct < 2; ++ct) {
; #pragma unroll
;                     for (int e = 0; e < 16; ++e) st[kt][ct][e] *= gs[e >> 2][e & 3];
;                     st[kt][ct] = __builtin_amdgcn_mfma_f32_32x32x16_bf16(au, ufr[ct], st[kt][ct], 0, 0, 0);
;                     if (role) st[kt][ct] = __builtin_amdgcn_mfma_f32_32x32x16_bf16(av, vfr[ct], st[kt][ct], 0, 0, 0); } }
.LBB0_719:
	v_add_u32_e32 v88, s98, v161
	ds_read_b128 v[64:67], v88 offset:14400
	ds_read_b128 v[68:71], v88 offset:14432
	ds_read_b128 v[72:75], v88 offset:14336
	ds_read_b128 v[76:79], v88 offset:14368
	v_mad_u32_u24 v84, v158, s57, v88
	ds_read_b128 v[80:83], v84 offset:9216
	ds_read_b128 v[84:87], v84 offset:11776
	s_waitcnt lgkmcnt(4)
	v_pk_mul_f32 v[12:13], v[12:13], v[68:69]
	v_pk_mul_f32 v[8:9], v[8:9], v[64:65]
	s_waitcnt lgkmcnt(2)
	v_pk_mul_f32 v[4:5], v[4:5], v[76:77]
	v_pk_mul_f32 v[14:15], v[14:15], v[70:71]
	v_pk_mul_f32 v[10:11], v[10:11], v[66:67]
	v_pk_mul_f32 v[2:3], v[2:3], v[74:75]
	v_pk_mul_f32 v[28:29], v[28:29], v[68:69]
	v_pk_mul_f32 v[24:25], v[24:25], v[64:65]
	v_pk_mul_f32 v[20:21], v[20:21], v[76:77]
	v_pk_mul_f32 v[30:31], v[30:31], v[70:71]
	v_pk_mul_f32 v[26:27], v[26:27], v[66:67]
	v_pk_mul_f32 v[18:19], v[18:19], v[74:75]
	ds_read_b128 v[64:67], v88 offset:14528
	ds_read_b128 v[68:71], v88 offset:14560
	ds_read_b128 v[74:77], v88 offset:14464
	ds_read_b128 v[88:91], v88 offset:14496
	v_pk_mul_f32 v[6:7], v[6:7], v[78:79]
	v_pk_mul_f32 v[0:1], v[0:1], v[72:73]
	v_pk_mul_f32 v[22:23], v[22:23], v[78:79]
	v_pk_mul_f32 v[16:17], v[16:17], v[72:73]
	s_waitcnt lgkmcnt(2)
	v_pk_mul_f32 v[44:45], v[44:45], v[68:69]
	v_pk_mul_f32 v[40:41], v[40:41], v[64:65]
	s_waitcnt lgkmcnt(0)
	v_pk_mul_f32 v[36:37], v[36:37], v[88:89]
	v_pk_mul_f32 v[46:47], v[46:47], v[70:71]
	v_pk_mul_f32 v[42:43], v[42:43], v[66:67]
	v_pk_mul_f32 v[38:39], v[38:39], v[90:91]
	v_pk_mul_f32 v[34:35], v[34:35], v[76:77]
	v_pk_mul_f32 v[32:33], v[32:33], v[74:75]
	v_pk_mul_f32 v[60:61], v[60:61], v[68:69]
	v_pk_mul_f32 v[56:57], v[56:57], v[64:65]
	v_pk_mul_f32 v[52:53], v[52:53], v[88:89]
	v_pk_mul_f32 v[62:63], v[62:63], v[70:71]
	v_pk_mul_f32 v[58:59], v[58:59], v[66:67]
	v_pk_mul_f32 v[54:55], v[54:55], v[90:91]
	v_pk_mul_f32 v[50:51], v[50:51], v[76:77]
	v_pk_mul_f32 v[48:49], v[48:49], v[74:75]
	v_mfma_f32_32x32x16_bf16 v[0:15], v[80:83], v[100:103], v[0:15]
	s_waitcnt lgkmcnt(0)
	s_add_i32 s62, s62, 16
	s_add_i32 s65, s65, -16
	s_cmpk_eq_i32 s62, 0x200
	v_mfma_f32_32x32x16_bf16 v[16:31], v[80:83], v[96:99], v[16:31]
	v_mfma_f32_32x32x16_bf16 v[32:47], v[84:87], v[100:103], v[32:47]
	v_mfma_f32_32x32x16_bf16 v[48:63], v[84:87], v[96:99], v[48:63]
	s_cbranch_scc1 .LBB0_715
.LBB0_720:
	s_waitcnt vmcnt(0) lgkmcnt(0)
	s_add_i32 s98, s42, 0x11400
	s_barrier
	v_mov_b32_e32 v159, v124
	v_cmp_gt_u32_e32 vcc, 32, v159
	v_and_b32_e32 v158, 31, v159
	v_ashrrev_i32_e32 v160, 5, v159
	v_lshlrev_b32_e32 v161, 4, v160
	s_add_i32 s67, s25, s62
	s_add_i32 s2, s65, 16
	s_and_b64 s[0:1], s[28:29], exec
	s_cselect_b32 s36, s67, s2
	v_lshlrev_b32_e32 v96, 3, v160
	v_mov_b32_e32 v162, s98
	s_ashr_i32 s37, s36, 31
	v_mad_u32_u24 v163, v158, s54, v162
	s_barrier
	v_add_u32_e32 v104, v163, v96
	ds_read2_b64 v[64:67], v104 offset1:2
	v_cvt_pk_bf16_f32 v68, v0, v1
	v_cvt_pk_bf16_f32 v69, v2, v3
	v_cvt_pk_bf16_f32 v70, v4, v5
	v_cvt_pk_bf16_f32 v71, v6, v7
	s_nop 1
	s_waitcnt lgkmcnt(0)
	v_mfma_f32_32x32x16_bf16 v[80:95], v[64:67], v[68:71], 0
	v_cvt_pk_bf16_f32 v68, v16, v17
	v_cvt_pk_bf16_f32 v69, v18, v19
	v_cvt_pk_bf16_f32 v70, v20, v21
	v_cvt_pk_bf16_f32 v71, v22, v23
	s_nop 1
	ds_read2_b64 v[96:99], v104 offset0:4 offset1:6
	v_cvt_pk_bf16_f32 v100, v8, v9
	v_cvt_pk_bf16_f32 v101, v10, v11
	v_cvt_pk_bf16_f32 v102, v12, v13
	v_cvt_pk_bf16_f32 v103, v14, v15
	s_nop 1
	v_mfma_f32_32x32x16_bf16 v[64:79], v[64:67], v[68:71], 0
	s_waitcnt lgkmcnt(0)
	v_mfma_f32_32x32x16_bf16 v[80:95], v[96:99], v[100:103], v[80:95]
	v_cvt_pk_bf16_f32 v100, v24, v25
	v_cvt_pk_bf16_f32 v101, v26, v27
	v_cvt_pk_bf16_f32 v102, v28, v29
	v_cvt_pk_bf16_f32 v103, v30, v31
	s_nop 1
	s_nop 0
	v_mfma_f32_32x32x16_bf16 v[64:79], v[96:99], v[100:103], v[64:79]
	ds_read2_b64 v[96:99], v104 offset0:8 offset1:10
	v_cvt_pk_bf16_f32 v100, v32, v33
	v_cvt_pk_bf16_f32 v101, v34, v35
	v_cvt_pk_bf16_f32 v102, v36, v37
	v_cvt_pk_bf16_f32 v103, v38, v39
	s_nop 1
	s_waitcnt lgkmcnt(0)
	v_mfma_f32_32x32x16_bf16 v[80:95], v[96:99], v[100:103], v[80:95]
	v_cvt_pk_bf16_f32 v100, v48, v49
	v_cvt_pk_bf16_f32 v101, v50, v51
	v_cvt_pk_bf16_f32 v102, v52, v53
	v_cvt_pk_bf16_f32 v103, v54, v55
	s_nop 1
	s_nop 0
	v_mfma_f32_32x32x16_bf16 v[64:79], v[96:99], v[100:103], v[64:79]
	ds_read2_b64 v[96:99], v104 offset0:12 offset1:14
	v_cvt_pk_bf16_f32 v100, v40, v41
	v_cvt_pk_bf16_f32 v101, v42, v43
	v_cvt_pk_bf16_f32 v102, v44, v45
	v_cvt_pk_bf16_f32 v103, v46, v47
	s_nop 1
	s_waitcnt lgkmcnt(0)
	v_mfma_f32_32x32x16_bf16 v[80:95], v[96:99], v[100:103], v[80:95]
	v_cvt_pk_bf16_f32 v100, v56, v57
	v_cvt_pk_bf16_f32 v101, v58, v59
	v_cvt_pk_bf16_f32 v102, v60, v61
	v_cvt_pk_bf16_f32 v103, v62, v63
	s_nop 1
	s_nop 0
	v_mfma_f32_32x32x16_bf16 v[64:79], v[96:99], v[100:103], v[64:79]
	v_add_u32_e32 v112, 0x1000, v162
	ds_read2_b32 v[110:111], v112 offset0:164 offset1:200
	s_nop 7
	v_mov_b32_e32 v96, v80
	v_mov_b32_e32 v122, v80
	v_mov_b32_e32 v97, v64
	v_mov_b32_e32 v123, v64
	v_mov_b32_e32 v98, v81
	v_mov_b32_e32 v164, v81
	v_mov_b32_e32 v99, v65
	v_mov_b32_e32 v165, v65
	v_permlane32_swap_b32_e32 v96, v122
	v_permlane32_swap_b32_e32 v97, v123
	v_permlane32_swap_b32_e32 v98, v164
	v_permlane32_swap_b32_e32 v99, v165
	v_mov_b32_e32 v106, v82
	v_mov_b32_e32 v168, v82
	v_mov_b32_e32 v107, v66
	v_mov_b32_e32 v169, v66
	v_permlane32_swap_b32_e32 v106, v168
	s_nop 0
	v_permlane32_swap_b32_e32 v107, v169
	s_waitcnt lgkmcnt(0)
; #define LAS __attribute__((address_space(3)))
; template <int role> __device__ __forceinline__ void ph_scan1m_r(Ctx& C) {
;     ...
;             for (int t = 1; t < 16; ++t) { f32x2 a = u2[t]; float clast = 0.f;
; #pragma unroll
;                 for (int q = 0; q < 4; ++q) { const int smin = q < 2 ? 8 * q : 8 * (q - 2) + 1;
;                     if (smin < t) { const f32x4 cf = *(const LAS f32x4*)(MT + t * 36 + 4 * q);
; #pragma unroll
;                         for (int e = 0; e < 4; ++e) { const int sl = 4 * q + e, st_ = sl < 8 ? 2 * sl : 2 * (sl - 8) + 1; if (st_ == t - 1) clast = cf[e]; else if (st_ < t) a += u2[st_] * cf[e]; } } }
;                 a += u2[t - 1] * clast;
;                 u2[t] = a; }
	v_pk_fma_f32 v[98:99], v[110:111], v[96:97], v[98:99] op_sel_hi:[0,1,1]
	v_mov_b32_e32 v110, v111
	v_pk_fma_f32 v[106:107], v[110:111], v[96:97], v[106:107] op_sel_hi:[0,1,1]
	ds_read_b32 v166, v162 offset:4928
	ds_read_b64 v[172:173], v162 offset:5040
	ds_read_b32 v174, v162 offset:5072
	ds_read2_b64 v[110:113], v112 offset0:136 offset1:140
	ds_read_b96 v[114:116], v162 offset:5328
	v_mov_b32_e32 v108, v83
	v_mov_b32_e32 v170, v83
	v_mov_b32_e32 v109, v67
	v_mov_b32_e32 v171, v67
	v_permlane32_swap_b32_e32 v108, v170
	s_nop 0
	v_permlane32_swap_b32_e32 v109, v171
	s_waitcnt lgkmcnt(4)
	v_pk_fma_f32 v[106:107], v[98:99], v[166:167], v[106:107] op_sel_hi:[1,0,1]
	s_waitcnt lgkmcnt(3)
	v_pk_fma_f32 v[108:109], v[172:173], v[96:97], v[108:109] op_sel_hi:[0,1,1]
	s_waitcnt lgkmcnt(1)
	v_pk_fma_f32 v[122:123], v[110:111], v[96:97], v[122:123] op_sel_hi:[0,1,1]
	v_pk_fma_f32 v[108:109], v[98:99], v[174:175], v[108:109] op_sel_hi:[1,0,1]
	v_pk_fma_f32 v[110:111], v[106:107], v[110:111], v[122:123] op_sel:[0,1,0]
	ds_read_b64 v[122:123], v162 offset:5360
	v_pk_fma_f32 v[108:109], v[172:173], v[106:107], v[108:109] op_sel:[1,0,0]
	v_pk_fma_f32 v[110:111], v[98:99], v[112:113], v[110:111] op_sel_hi:[1,0,1]
	ds_read_b96 v[172:174], v162 offset:5648
	v_pk_fma_f32 v[110:111], v[112:113], v[108:109], v[110:111] op_sel:[1,0,0]
	s_waitcnt lgkmcnt(2)
	v_pk_fma_f32 v[112:113], v[114:115], v[96:97], v[164:165] op_sel_hi:[0,1,1]
	ds_read_b96 v[164:166], v162 offset:5472
	v_pk_fma_f32 v[112:113], v[106:107], v[114:115], v[112:113] op_sel:[0,1,0]
	v_mov_b32_e32 v114, v116
	s_waitcnt lgkmcnt(2)
	v_pk_fma_f32 v[112:113], v[98:99], v[122:123], v[112:113] op_sel_hi:[1,0,1]
	v_mov_b32_e32 v176, v84
	v_pk_fma_f32 v[112:113], v[108:109], v[122:123], v[112:113] op_sel:[0,1,0]
	s_waitcnt lgkmcnt(0)
	v_pk_fma_f32 v[122:123], v[164:165], v[96:97], v[168:169] op_sel_hi:[0,1,1]
	v_pk_fma_f32 v[112:113], v[114:115], v[110:111], v[112:113] op_sel_hi:[0,1,1]
	ds_read_b96 v[114:116], v162 offset:5504
	v_pk_fma_f32 v[122:123], v[106:107], v[164:165], v[122:123] op_sel:[0,1,0]
	v_mov_b32_e32 v164, v166
	v_pk_fma_f32 v[122:123], v[164:165], v[110:111], v[122:123] op_sel_hi:[0,1,1]
	ds_read_b128 v[164:167], v162 offset:5616
	s_waitcnt lgkmcnt(1)
	v_pk_fma_f32 v[122:123], v[98:99], v[114:115], v[122:123] op_sel_hi:[1,0,1]
	v_mov_b32_e32 v120, v84
	v_pk_fma_f32 v[114:115], v[108:109], v[114:115], v[122:123] op_sel:[0,1,0]
	v_mov_b32_e32 v177, v68
	v_pk_fma_f32 v[114:115], v[116:117], v[112:113], v[114:115] op_sel_hi:[0,1,1]
	s_waitcnt lgkmcnt(0)
	v_pk_fma_f32 v[116:117], v[164:165], v[96:97], v[170:171] op_sel_hi:[0,1,1]
	v_pk_fma_f32 v[116:117], v[106:107], v[164:165], v[116:117] op_sel:[0,1,0]
	ds_read_b128 v[168:171], v162 offset:5760
	v_pk_fma_f32 v[116:117], v[110:111], v[166:167], v[116:117] op_sel_hi:[1,0,1]
	v_mov_b32_e32 v121, v68
	v_pk_fma_f32 v[116:117], v[98:99], v[172:173], v[116:117] op_sel_hi:[1,0,1]
	v_mov_b32_e32 v122, v174
	v_pk_fma_f32 v[116:117], v[108:109], v[172:173], v[116:117] op_sel:[0,1,0]
	v_permlane32_swap_b32_e32 v176, v120
	v_permlane32_swap_b32_e32 v177, v121
	v_pk_fma_f32 v[116:117], v[122:123], v[112:113], v[116:117] op_sel_hi:[0,1,1]
	v_mov_b32_e32 v122, v167
	v_pk_fma_f32 v[116:117], v[122:123], v[114:115], v[116:117] op_sel_hi:[0,1,1]
	s_waitcnt lgkmcnt(0)
	v_pk_fma_f32 v[122:123], v[168:169], v[96:97], v[176:177] op_sel_hi:[0,1,1]
	ds_read_b128 v[164:167], v162 offset:5792
	v_pk_fma_f32 v[122:123], v[106:107], v[168:169], v[122:123] op_sel:[0,1,0]
	v_mov_b32_e32 v168, v171
	v_pk_fma_f32 v[122:123], v[110:111], v[170:171], v[122:123] op_sel_hi:[1,0,1]
	v_mov_b32_e32 v178, v85
	v_pk_fma_f32 v[122:123], v[168:169], v[114:115], v[122:123] op_sel_hi:[0,1,1]
	ds_read_b128 v[168:171], v162 offset:5904
	s_waitcnt lgkmcnt(1)
	v_pk_fma_f32 v[122:123], v[98:99], v[164:165], v[122:123] op_sel_hi:[1,0,1]
	v_mov_b32_e32 v118, v85
	v_mov_b32_e32 v179, v69
	v_mov_b32_e32 v119, v69
	v_pk_fma_f32 v[122:123], v[108:109], v[164:165], v[122:123] op_sel:[0,1,0]
	v_permlane32_swap_b32_e32 v178, v118
	v_permlane32_swap_b32_e32 v179, v119
	v_pk_fma_f32 v[122:123], v[112:113], v[166:167], v[122:123] op_sel_hi:[1,0,1]
	v_mov_b32_e32 v164, v167
	v_pk_fma_f32 v[122:123], v[164:165], v[116:117], v[122:123] op_sel_hi:[0,1,1]
	s_waitcnt lgkmcnt(0)
	v_pk_fma_f32 v[164:165], v[168:169], v[96:97], v[178:179] op_sel_hi:[0,1,1]
	v_pk_fma_f32 v[164:165], v[106:107], v[168:169], v[164:165] op_sel:[0,1,0]
	v_mov_b32_e32 v180, v86
	v_pk_fma_f32 v[168:169], v[110:111], v[170:171], v[164:165] op_sel_hi:[1,0,1]
	ds_read_b128 v[164:167], v162 offset:5936
	v_mov_b32_e32 v170, v171
	v_pk_fma_f32 v[172:173], v[170:171], v[114:115], v[168:169] op_sel_hi:[0,1,1]
	v_add_u32_e32 v168, 0x1400, v162
	ds_read2_b32 v[174:175], v168 offset0:200 offset1:236
	ds_read_b128 v[168:171], v162 offset:6048
	s_waitcnt lgkmcnt(2)
	v_pk_fma_f32 v[172:173], v[98:99], v[164:165], v[172:173] op_sel_hi:[1,0,1]
	v_mov_b32_e32 v102, v86
	v_pk_fma_f32 v[164:165], v[108:109], v[164:165], v[172:173] op_sel:[0,1,0]
	v_mov_b32_e32 v181, v70
	v_mov_b32_e32 v103, v70
	v_pk_fma_f32 v[164:165], v[112:113], v[166:167], v[164:165] op_sel_hi:[1,0,1]
	v_mov_b32_e32 v166, v167
	v_permlane32_swap_b32_e32 v180, v102
	v_permlane32_swap_b32_e32 v181, v103
	v_pk_fma_f32 v[164:165], v[166:167], v[116:117], v[164:165] op_sel_hi:[0,1,1]
	s_waitcnt lgkmcnt(1)
	v_pk_fma_f32 v[176:177], v[174:175], v[122:123], v[164:165] op_sel_hi:[0,1,1]
	s_waitcnt lgkmcnt(0)
; #define LAS __attribute__((address_space(3)))
; template <int role> __device__ __forceinline__ void ph_scan1m_r(Ctx& C) {
;     ...
;             for (int t = 1; t < 16; ++t) { f32x2 a = u2[t]; float clast = 0.f;
; #pragma unroll
;                 for (int q = 0; q < 4; ++q) { const int smin = q < 2 ? 8 * q : 8 * (q - 2) + 1;
;                     if (smin < t) { const f32x4 cf = *(const LAS f32x4*)(MT + t * 36 + 4 * q);
; #pragma unroll
;                         for (int e = 0; e < 4; ++e) { const int sl = 4 * q + e, st_ = sl < 8 ? 2 * sl : 2 * (sl - 8) + 1; if (st_ == t - 1) clast = cf[e]; else if (st_ < t) a += u2[st_] * cf[e]; } } }
;                 a += u2[t - 1] * clast;
;                 u2[t] = a; }
	v_pk_fma_f32 v[164:165], v[168:169], v[96:97], v[180:181] op_sel_hi:[0,1,1]
	v_pk_fma_f32 v[164:165], v[106:107], v[168:169], v[164:165] op_sel:[0,1,0]
	ds_read_b32 v172, v162 offset:6096
	v_pk_fma_f32 v[168:169], v[110:111], v[170:171], v[164:165] op_sel_hi:[1,0,1]
	ds_read_b128 v[164:167], v162 offset:6080
	v_mov_b32_e32 v170, v171
	v_pk_fma_f32 v[168:169], v[114:115], v[170:171], v[168:169] op_sel_hi:[1,0,1]
	v_mov_b32_e32 v170, v175
	v_pk_fma_f32 v[168:169], v[170:171], v[122:123], v[168:169] op_sel_hi:[0,1,1]
	s_waitcnt lgkmcnt(0)
	v_pk_fma_f32 v[168:169], v[98:99], v[164:165], v[168:169] op_sel_hi:[1,0,1]
	v_mov_b32_e32 v182, v87
	v_pk_fma_f32 v[164:165], v[108:109], v[164:165], v[168:169] op_sel:[0,1,0]
	ds_read_b128 v[168:171], v162 offset:6192
	v_mov_b32_e32 v100, v87
	v_mov_b32_e32 v183, v71
	v_mov_b32_e32 v101, v71
	v_pk_fma_f32 v[164:165], v[112:113], v[166:167], v[164:165] op_sel_hi:[1,0,1]
	v_mov_b32_e32 v166, v167
	v_permlane32_swap_b32_e32 v182, v100
	v_permlane32_swap_b32_e32 v183, v101
	v_pk_fma_f32 v[164:165], v[116:117], v[166:167], v[164:165] op_sel_hi:[1,0,1]
	s_nop 0
	v_pk_fma_f32 v[178:179], v[172:173], v[176:177], v[164:165] op_sel_hi:[0,1,1]
	ds_read_b64 v[172:173], v162 offset:6208
	s_waitcnt lgkmcnt(1)
	v_pk_fma_f32 v[164:165], v[168:169], v[96:97], v[182:183] op_sel_hi:[0,1,1]
	v_pk_fma_f32 v[164:165], v[106:107], v[168:169], v[164:165] op_sel:[0,1,0]
	s_nop 0
	v_pk_fma_f32 v[168:169], v[110:111], v[170:171], v[164:165] op_sel_hi:[1,0,1]
	ds_read_b128 v[164:167], v162 offset:6224
	v_mov_b32_e32 v170, v171
	v_pk_fma_f32 v[168:169], v[114:115], v[170:171], v[168:169] op_sel_hi:[1,0,1]
	ds_read_b32 v170, v162 offset:6240
	s_waitcnt lgkmcnt(2)
	v_pk_fma_f32 v[168:169], v[122:123], v[172:173], v[168:169] op_sel_hi:[1,0,1]
	s_waitcnt lgkmcnt(1)
	v_mov_b32_e32 v174, v167
	v_pk_fma_f32 v[168:169], v[98:99], v[164:165], v[168:169] op_sel_hi:[1,0,1]
	s_nop 0
	v_pk_fma_f32 v[164:165], v[108:109], v[164:165], v[168:169] op_sel:[0,1,0]
	s_nop 0
	v_pk_fma_f32 v[168:169], v[112:113], v[166:167], v[164:165] op_sel_hi:[1,0,1]
	ds_read_b128 v[164:167], v162 offset:6336
	v_pk_fma_f32 v[168:169], v[116:117], v[174:175], v[168:169] op_sel_hi:[1,0,1]
	s_waitcnt lgkmcnt(1)
	v_pk_fma_f32 v[168:169], v[170:171], v[176:177], v[168:169] op_sel_hi:[0,1,1]
	v_pk_fma_f32 v[180:181], v[172:173], v[178:179], v[168:169] op_sel:[1,0,0]
	v_add_u32_e32 v172, 0x1800, v162
	ds_read2_b64 v[172:175], v172 offset0:26 offset1:30
	ds_read_b128 v[168:171], v162 offset:6368
	s_waitcnt lgkmcnt(2)
	v_pk_fma_f32 v[120:121], v[164:165], v[96:97], v[120:121] op_sel_hi:[0,1,1]
	v_pk_fma_f32 v[120:121], v[106:107], v[164:165], v[120:121] op_sel:[0,1,0]
	v_mov_b32_e32 v164, v167
	v_pk_fma_f32 v[120:121], v[110:111], v[166:167], v[120:121] op_sel_hi:[1,0,1]
	s_nop 0
	v_pk_fma_f32 v[120:121], v[114:115], v[164:165], v[120:121] op_sel_hi:[1,0,1]
	ds_read_b128 v[164:167], v162 offset:6480
	s_waitcnt lgkmcnt(2)
	v_pk_fma_f32 v[120:121], v[122:123], v[172:173], v[120:121] op_sel_hi:[1,0,1]
	s_nop 0
	v_pk_fma_f32 v[120:121], v[172:173], v[178:179], v[120:121] op_sel:[1,0,0]
	s_waitcnt lgkmcnt(1)
	v_pk_fma_f32 v[120:121], v[98:99], v[168:169], v[120:121] op_sel_hi:[1,0,1]
	s_nop 0
	v_pk_fma_f32 v[120:121], v[108:109], v[168:169], v[120:121] op_sel:[0,1,0]
	v_mov_b32_e32 v168, v171
	v_pk_fma_f32 v[120:121], v[112:113], v[170:171], v[120:121] op_sel_hi:[1,0,1]
	s_nop 0
	v_pk_fma_f32 v[120:121], v[116:117], v[168:169], v[120:121] op_sel_hi:[1,0,1]
	ds_read_b96 v[168:170], v162 offset:6496
	s_waitcnt lgkmcnt(1)
	v_pk_fma_f32 v[118:119], v[164:165], v[96:97], v[118:119] op_sel_hi:[0,1,1]
	v_pk_fma_f32 v[120:121], v[176:177], v[174:175], v[120:121] op_sel_hi:[1,0,1]
	v_pk_fma_f32 v[118:119], v[106:107], v[164:165], v[118:119] op_sel:[0,1,0]
	v_pk_fma_f32 v[172:173], v[174:175], v[180:181], v[120:121] op_sel:[1,0,0]
	v_pk_fma_f32 v[164:165], v[110:111], v[166:167], v[118:119] op_sel_hi:[1,0,1]
	ds_read_b128 v[118:121], v162 offset:6512
	v_mov_b32_e32 v166, v167
	v_pk_fma_f32 v[164:165], v[114:115], v[166:167], v[164:165] op_sel_hi:[1,0,1]
	ds_read_b64 v[166:167], v162 offset:6528
	s_waitcnt lgkmcnt(2)
	v_pk_fma_f32 v[164:165], v[122:123], v[168:169], v[164:165] op_sel_hi:[1,0,1]
	s_nop 0
	v_pk_fma_f32 v[164:165], v[178:179], v[168:169], v[164:165] op_sel:[0,1,0]
	s_waitcnt lgkmcnt(1)
	v_pk_fma_f32 v[164:165], v[98:99], v[118:119], v[164:165] op_sel_hi:[1,0,1]
	s_nop 0
	v_pk_fma_f32 v[118:119], v[108:109], v[118:119], v[164:165] op_sel:[0,1,0]
	s_nop 0
	v_pk_fma_f32 v[118:119], v[112:113], v[120:121], v[118:119] op_sel_hi:[1,0,1]
	v_mov_b32_e32 v120, v121
	v_pk_fma_f32 v[118:119], v[116:117], v[120:121], v[118:119] op_sel_hi:[1,0,1]
	s_waitcnt lgkmcnt(0)
	v_pk_fma_f32 v[164:165], v[176:177], v[166:167], v[118:119] op_sel_hi:[1,0,1]
	ds_read_b128 v[118:121], v162 offset:6624
	v_pk_fma_f32 v[164:165], v[166:167], v[180:181], v[164:165] op_sel:[1,0,0]
	v_mov_b32_e32 v166, v170
	v_pk_fma_f32 v[168:169], v[166:167], v[172:173], v[164:165] op_sel_hi:[0,1,1]
	ds_read_b96 v[164:166], v162 offset:6640
	s_waitcnt lgkmcnt(1)
	v_pk_fma_f32 v[102:103], v[118:119], v[96:97], v[102:103] op_sel_hi:[0,1,1]
	v_pk_fma_f32 v[102:103], v[106:107], v[118:119], v[102:103] op_sel:[0,1,0]
	v_mov_b32_e32 v118, v121
	v_pk_fma_f32 v[102:103], v[110:111], v[120:121], v[102:103] op_sel_hi:[1,0,1]
	s_nop 0
	v_pk_fma_f32 v[102:103], v[114:115], v[118:119], v[102:103] op_sel_hi:[1,0,1]
	ds_read_b128 v[118:121], v162 offset:6656
	s_waitcnt lgkmcnt(1)
; #define LAS __attribute__((address_space(3)))
; __device__ __forceinline__ unsigned cvt_pk_bf16(float lo, float hi) { unsigned r; asm volatile("v_cvt_pk_bf16_f32 %0, %1, %2" : "=v"(r) : "v"(lo), "v"(hi)); return r; }
; template <int role> __device__ __forceinline__ void ph_scan1m_r(Ctx& C) {
;     ...
;                 u2[t] = a; }
;             bf16x8 ufr[2];
;             ufr[0] = pack8s(hh ? u2[1].x : u2[0].x, hh ? u2[3].x : u2[2].x, hh ? u2[5].x : u2[4].x, hh ? u2[7].x : u2[6].x, hh ? u2[9].x : u2[8].x, hh ? u2[11].x : u2[10].x, hh ? u2[13].x : u2[12].x, hh ? u2[15].x : u2[14].x);
;             ufr[1] = pack8s(hh ? u2[1].y : u2[0].y, hh ? u2[3].y : u2[2].y, hh ? u2[5].y : u2[4].y, hh ? u2[7].y : u2[6].y, hh ? u2[9].y : u2[8].y, hh ? u2[11].y : u2[10].y, hh ? u2[13].y : u2[12].y, hh ? u2[15].y : u2[14].y);
;             __builtin_amdgcn_sched_barrier(0);
;             { const f32x4 m0 = *(const LAS f32x4*)(MT + r31 * 36 + 8 * hh), m1 = *(const LAS f32x4*)(MT + r31 * 36 + 4 + 8 * hh); const bf16x8 af = pack8s(m0[0], m0[1], m0[2], m0[3], m1[0], m1[1], m1[2], m1[3]);
; #pragma unroll
;               for (int ct = 0; ct < 2; ++ct) ya[ct] = __builtin_amdgcn_mfma_f32_32x32x16_bf16(af, ufr[ct], ya[ct], 0, 0, 0); }
;             { LAS bf16* ys = (LAS bf16*)MT;
; #pragma unroll
;               for (int ct = 0; ct < 2; ++ct)
; #pragma unroll
;                   for (int e = 0; e < 8; e += 2) { const unsigned pw = pg8::cvt_pk_bf16(ya[ct][8 + e], ya[ct][9 + e]); const int t = (e & 3) + 4 * hh + 8 * (e >> 2); LAS bf16* d = ys + t * 72 + 32 * ct + r31; d[0] = (bf16)pw; d[72] = (bf16)(pw >> 16); }
;               asm volatile("s_waitcnt lgkmcnt(0)" ::: "memory");
; #pragma unroll
;               for (int i = 0; i < 2; ++i) { const int t = (lane >> 3) + 8 * i; const u32x4 w = *(const LAS u32x4*)(ys + t * 72 + 8 * (lane & 7)); *(u32x4*)(g_out + zoff + rowu + (long)t * dix + 8 * (lane & 7)) = w; }
;               asm volatile("s_waitcnt lgkmcnt(0)" ::: "memory"); }
	v_pk_fma_f32 v[102:103], v[122:123], v[164:165], v[102:103] op_sel_hi:[1,0,1]
	s_nop 0
	v_pk_fma_f32 v[102:103], v[178:179], v[164:165], v[102:103] op_sel:[0,1,0]
	v_mov_b32_e32 v164, v166
	v_pk_fma_f32 v[102:103], v[164:165], v[172:173], v[102:103] op_sel_hi:[0,1,1]
	ds_read_b96 v[164:166], v162 offset:6672
	s_waitcnt lgkmcnt(1)
	v_pk_fma_f32 v[102:103], v[98:99], v[118:119], v[102:103] op_sel_hi:[1,0,1]
	s_nop 0
	v_pk_fma_f32 v[102:103], v[108:109], v[118:119], v[102:103] op_sel:[0,1,0]
	v_mov_b32_e32 v118, v121
	v_pk_fma_f32 v[102:103], v[112:113], v[120:121], v[102:103] op_sel_hi:[1,0,1]
	s_nop 0
	v_pk_fma_f32 v[102:103], v[116:117], v[118:119], v[102:103] op_sel_hi:[1,0,1]
	ds_read_b128 v[118:121], v162 offset:6768
	s_waitcnt lgkmcnt(1)
	v_pk_fma_f32 v[102:103], v[176:177], v[164:165], v[102:103] op_sel_hi:[1,0,1]
	s_nop 0
	v_pk_fma_f32 v[102:103], v[180:181], v[164:165], v[102:103] op_sel:[0,1,0]
	v_mov_b32_e32 v164, v166
	v_pk_fma_f32 v[170:171], v[164:165], v[168:169], v[102:103] op_sel_hi:[0,1,1]
	ds_read_b128 v[164:167], v162 offset:6784
	s_waitcnt lgkmcnt(1)
	v_pk_fma_f32 v[100:101], v[118:119], v[96:97], v[100:101] op_sel_hi:[0,1,1]
	v_pk_fma_f32 v[100:101], v[106:107], v[118:119], v[100:101] op_sel:[0,1,0]
	v_mov_b32_e32 v102, v121
	v_pk_fma_f32 v[100:101], v[110:111], v[120:121], v[100:101] op_sel_hi:[1,0,1]
	v_cndmask_b32_e32 v96, v98, v96, vcc
	v_pk_fma_f32 v[118:119], v[114:115], v[102:103], v[100:101] op_sel_hi:[1,0,1]
	ds_read_b128 v[100:103], v162 offset:6800
	s_waitcnt lgkmcnt(1)
	v_pk_fma_f32 v[118:119], v[122:123], v[164:165], v[118:119] op_sel_hi:[1,0,1]
	v_cndmask_b32_e32 v107, v109, v107, vcc
	v_pk_fma_f32 v[118:119], v[178:179], v[164:165], v[118:119] op_sel:[0,1,0]
	s_nop 0
	v_pk_fma_f32 v[164:165], v[166:167], v[172:173], v[118:119] op_sel_hi:[0,1,1]
	ds_read_b96 v[118:120], v162 offset:6816
	s_waitcnt lgkmcnt(1)
	v_pk_fma_f32 v[164:165], v[98:99], v[100:101], v[164:165] op_sel_hi:[1,0,1]
	v_cndmask_b32_e32 v98, v108, v106, vcc
	v_pk_fma_f32 v[100:101], v[108:109], v[100:101], v[164:165] op_sel:[0,1,0]
	v_cndmask_b32_e32 v106, v112, v110, vcc
	v_pk_fma_f32 v[100:101], v[112:113], v[102:103], v[100:101] op_sel_hi:[1,0,1]
	v_mov_b32_e32 v102, v103
	v_pk_fma_f32 v[100:101], v[116:117], v[102:103], v[100:101] op_sel_hi:[1,0,1]
	s_waitcnt lgkmcnt(0)
	v_mov_b32_e32 v102, v120
	v_pk_fma_f32 v[100:101], v[176:177], v[118:119], v[100:101] op_sel_hi:[1,0,1]
	v_cndmask_b32_e32 v108, v116, v114, vcc
	v_pk_fma_f32 v[100:101], v[180:181], v[118:119], v[100:101] op_sel:[0,1,0]
	v_cndmask_b32_e32 v110, v176, v122, vcc
	v_pk_fma_f32 v[100:101], v[102:103], v[168:169], v[100:101] op_sel_hi:[0,1,1]
	v_mov_b32_e32 v102, v167
	v_pk_fma_f32 v[118:119], v[102:103], v[170:171], v[100:101] op_sel_hi:[0,1,1]
	v_cndmask_b32_e32 v112, v180, v178, vcc
	v_cndmask_b32_e32 v114, v168, v172, vcc
	v_cndmask_b32_e32 v116, v118, v170, vcc
	v_cvt_pk_bf16_f32 v100, v96, v98
	v_cvt_pk_bf16_f32 v101, v106, v108
	v_cvt_pk_bf16_f32 v102, v110, v112
	v_cvt_pk_bf16_f32 v103, v114, v116
	s_nop 1
	v_cndmask_b32_e32 v106, v99, v97, vcc
	v_cndmask_b32_e32 v108, v113, v111, vcc
	v_cndmask_b32_e32 v109, v117, v115, vcc
	v_cndmask_b32_e32 v110, v177, v123, vcc
	v_cndmask_b32_e32 v111, v181, v179, vcc
	v_cndmask_b32_e32 v112, v169, v173, vcc
	v_cndmask_b32_e32 v113, v119, v171, vcc
	v_cvt_pk_bf16_f32 v96, v106, v107
	v_cvt_pk_bf16_f32 v97, v108, v109
	v_cvt_pk_bf16_f32 v98, v110, v111
	v_cvt_pk_bf16_f32 v99, v112, v113
	s_nop 1
	v_mad_u64_u32 v[110:111], s[0:1], v160, 24, v[104:105]
	ds_read_b128 v[106:109], v110 offset:4608
	ds_read_b128 v[110:113], v110 offset:4624
	s_lshl_b64 s[0:1], s[36:37], 11
	s_add_u32 s0, s63, s0
	s_addc_u32 s1, s64, s1
	s_waitcnt lgkmcnt(0)
	s_barrier
	v_cvt_pk_bf16_f32 v114, v106, v107
	v_cvt_pk_bf16_f32 v115, v108, v109
	v_cvt_pk_bf16_f32 v116, v110, v111
	v_cvt_pk_bf16_f32 v117, v112, v113
	s_nop 1
	s_nop 0
	v_mfma_f32_32x32x16_bf16 v[80:95], v[114:117], v[100:103], v[80:95]
	v_mfma_f32_32x32x16_bf16 v[64:79], v[114:117], v[96:99], v[64:79]
	s_nop 10
	v_mul_i32_i24_e32 v80, 0xffffff72, v158
	v_mul_lo_u32 v81, v160, s56
	v_add3_u32 v80, v163, v80, v81
	v_add_u32_e32 v80, 0xfffeec00, v80
	v_cvt_pk_bf16_f32 v64, v88, v89
	ds_write_b16 v80, v64 offset:4608
	ds_write_b16_d16_hi v80, v64 offset:4752
	v_cvt_pk_bf16_f32 v64, v90, v91
	ds_write_b16 v80, v64 offset:4896
	ds_write_b16_d16_hi v80, v64 offset:5040
	v_cvt_pk_bf16_f32 v64, v92, v93
	ds_write_b16 v80, v64 offset:5760
	ds_write_b16_d16_hi v80, v64 offset:5904
	v_cvt_pk_bf16_f32 v64, v94, v95
	ds_write_b16 v80, v64 offset:6048
	ds_write_b16_d16_hi v80, v64 offset:6192
	v_cvt_pk_bf16_f32 v64, v72, v73
	ds_write_b16 v80, v64 offset:4672
	ds_write_b16_d16_hi v80, v64 offset:4816
	v_cvt_pk_bf16_f32 v64, v74, v75
	ds_write_b16 v80, v64 offset:4960
	ds_write_b16_d16_hi v80, v64 offset:5104
	v_cvt_pk_bf16_f32 v64, v76, v77
	ds_write_b16 v80, v64 offset:5824
	ds_write_b16_d16_hi v80, v64 offset:5968
	v_cvt_pk_bf16_f32 v64, v78, v79
	ds_write_b16 v80, v64 offset:6112
	ds_write_b16_d16_hi v80, v64 offset:6256
	v_ashrrev_i32_e32 v76, 3, v159
	v_lshlrev_b32_e32 v64, 4, v159
	v_and_b32_e32 v104, 0x70, v64
	v_mul_lo_u32 v64, v76, s54
	s_waitcnt lgkmcnt(0)
	v_add3_u32 v70, s42, v104, v64
	ds_read_b128 v[64:67], v70 offset:4608
	v_ashrrev_i32_e32 v68, 31, v76
	v_lshl_add_u64 v[72:73], s[0:1], 0, v[104:105]
	v_mul_lo_u32 v71, s30, v68
	v_mul_lo_u32 v74, s31, v76
	v_mad_u64_u32 v[68:69], s[0:1], s30, v76, 0
	v_add3_u32 v69, v69, v71, v74
	v_lshl_add_u64 v[74:75], v[68:69], 1, v[72:73]
	ds_read_b128 v[68:71], v70 offset:5760
	s_waitcnt lgkmcnt(1)
	global_store_dwordx4 v[74:75], v[64:67], off
	s_nop 1
	v_add_u32_e32 v64, 8, v76
	v_ashrrev_i32_e32 v65, 31, v64
	v_mul_lo_u32 v66, s30, v65
	v_mul_lo_u32 v67, s31, v64
	v_mad_u64_u32 v[64:65], s[0:1], s30, v64, 0
	v_add3_u32 v65, v65, v66, v67
	v_lshl_add_u64 v[64:65], v[64:65], 1, v[72:73]
	s_waitcnt lgkmcnt(0)
	global_store_dwordx4 v[64:65], v[68:71], off
	s_waitcnt lgkmcnt(0)
	s_branch .LBB0_719
